# C + s_sleep removed from all poll loops
# baseline (speedup 1.0000x reference)
.LBB0_133:
	global_load_dword v17, v18, s[10:11] sc1
	global_load_dword v2, v18, s[12:13] sc1
	global_load_dword v3, v18, s[14:15] sc1
	global_load_dword v4, v18, s[16:17] sc1
	global_load_dword v5, v18, s[18:19] sc1
	global_load_dword v6, v18, s[20:21] sc1
	global_load_dword v7, v18, s[22:23] sc1
	global_load_dword v8, v18, s[38:39] sc1
	global_load_dword v9, v18, s[42:43] sc1
	global_load_dword v10, v18, s[44:45] sc1
	global_load_dword v11, v18, s[46:47] sc1
	global_load_dword v12, v18, s[48:49] sc1
	global_load_dword v13, v18, s[50:51] sc1
	global_load_dword v14, v18, s[52:53] sc1
	global_load_dword v15, v18, s[54:55] sc1
	global_load_dword v16, v18, s[56:57] sc1
	s_mov_b64 s[58:59], -1
	s_mov_b64 s[60:61], -1
	s_waitcnt vmcnt(14)
	v_add_u32_e32 v19, v2, v17
	s_waitcnt vmcnt(13)
	v_add_u32_e32 v19, v19, v3
	s_waitcnt vmcnt(12)
	v_add_u32_e32 v19, v19, v4
	s_waitcnt vmcnt(11)
	v_add_u32_e32 v19, v19, v5
	s_waitcnt vmcnt(10)
	v_add_u32_e32 v19, v19, v6
	s_waitcnt vmcnt(9)
	v_add_u32_e32 v19, v19, v7
	s_waitcnt vmcnt(8)
	v_add_u32_e32 v19, v19, v8
	s_waitcnt vmcnt(7)
	v_add_u32_e32 v19, v19, v9
	s_waitcnt vmcnt(6)
	v_add_u32_e32 v19, v19, v10
	s_waitcnt vmcnt(5)
	v_add_u32_e32 v19, v19, v11
	s_waitcnt vmcnt(4)
	v_add_u32_e32 v19, v19, v12
	s_waitcnt vmcnt(3)
	v_add_u32_e32 v19, v19, v13
	s_waitcnt vmcnt(2)
	v_add_u32_e32 v19, v19, v14
	s_waitcnt vmcnt(1)
	v_add_u32_e32 v19, v19, v15
	s_waitcnt vmcnt(0)
	v_add_u32_e32 v19, v19, v16
	v_cmp_eq_u32_e32 vcc, s0, v19
	s_cbranch_vccnz .LBB0_132
	s_and_b32 s3, s1, 0xff
	s_cmp_eq_u32 s3, 0
	s_mov_b64 s[62:63], -1
	s_cbranch_scc1 .LBB0_137
	s_and_b64 vcc, exec, s[62:63]
	s_cbranch_vccz .LBB0_132

.LBB0_151:
	s_and_b32 s1, s0, 0xff
	s_mov_b64 s[22:23], -1
	s_cmp_lg_u32 s1, 0
	s_mov_b64 s[42:43], -1
	s_cbranch_scc0 .LBB0_154
	s_and_b64 vcc, exec, s[42:43]
	s_cbranch_vccz .LBB0_150

.LBB0_168:
	s_and_b32 s1, s0, 0xff
	s_cmp_lg_u32 s1, 0
	s_mov_b64 s[38:39], -1
	s_cbranch_scc0 .LBB0_171
	s_mov_b64 s[42:43], -1
	s_and_b64 vcc, exec, s[38:39]
	s_cbranch_vccz .LBB0_167

.Lsk1_p1:
	s_waitcnt lgkmcnt(0)
	s_barrier
	s_setprio 1
	v_mfma_f32_16x16x32_bf16 v[126:129], v[130:133], v[162:165], v[126:129]
	v_mfma_f32_16x16x32_bf16 v[122:125], v[148:151], v[162:165], v[122:125]
	v_mfma_f32_16x16x32_bf16 v[118:121], v[130:133], v[170:173], v[118:121]
	v_mfma_f32_16x16x32_bf16 v[114:117], v[148:151], v[170:173], v[114:117]
	v_mfma_f32_16x16x32_bf16 v[110:113], v[130:133], v[178:181], v[110:113]
	v_mfma_f32_16x16x32_bf16 v[106:109], v[148:151], v[178:181], v[106:109]
	v_mfma_f32_16x16x32_bf16 v[102:105], v[130:133], v[186:189], v[102:105]
	v_mfma_f32_16x16x32_bf16 v[98:101], v[148:151], v[186:189], v[98:101]
	v_mfma_f32_16x16x32_bf16 v[126:129], v[134:137], v[166:169], v[126:129]
	v_mfma_f32_16x16x32_bf16 v[122:125], v[158:161], v[166:169], v[122:125]
	v_mfma_f32_16x16x32_bf16 v[118:121], v[134:137], v[174:177], v[118:121]
	v_mfma_f32_16x16x32_bf16 v[114:117], v[158:161], v[174:177], v[114:117]
	v_mfma_f32_16x16x32_bf16 v[110:113], v[134:137], v[182:185], v[110:113]
	v_mfma_f32_16x16x32_bf16 v[106:109], v[158:161], v[182:185], v[106:109]
	v_mfma_f32_16x16x32_bf16 v[102:105], v[134:137], v[190:193], v[102:105]
	v_mfma_f32_16x16x32_bf16 v[98:101], v[158:161], v[190:193], v[98:101]
	v_mfma_f32_16x16x32_bf16 v[62:65], v[194:197], v[162:165], v[62:65]
	v_mfma_f32_16x16x32_bf16 v[58:61], v[202:205], v[162:165], v[58:61]
	v_mfma_f32_16x16x32_bf16 v[54:57], v[194:197], v[170:173], v[54:57]
	v_mfma_f32_16x16x32_bf16 v[50:53], v[202:205], v[170:173], v[50:53]
	v_mfma_f32_16x16x32_bf16 v[46:49], v[194:197], v[178:181], v[46:49]
	v_mfma_f32_16x16x32_bf16 v[42:45], v[202:205], v[178:181], v[42:45]
	v_mfma_f32_16x16x32_bf16 v[38:41], v[194:197], v[186:189], v[38:41]
	v_mfma_f32_16x16x32_bf16 v[34:37], v[202:205], v[186:189], v[34:37]
	v_mfma_f32_16x16x32_bf16 v[62:65], v[198:201], v[166:169], v[62:65]
	v_mfma_f32_16x16x32_bf16 v[58:61], v[206:209], v[166:169], v[58:61]
	v_mfma_f32_16x16x32_bf16 v[54:57], v[198:201], v[174:177], v[54:57]
	v_mfma_f32_16x16x32_bf16 v[50:53], v[206:209], v[174:177], v[50:53]
	v_mfma_f32_16x16x32_bf16 v[46:49], v[198:201], v[182:185], v[46:49]
	v_mfma_f32_16x16x32_bf16 v[42:45], v[206:209], v[182:185], v[42:45]
	v_mfma_f32_16x16x32_bf16 v[38:41], v[198:201], v[190:193], v[38:41]
	v_mfma_f32_16x16x32_bf16 v[34:37], v[206:209], v[190:193], v[34:37]
	s_setprio 0
	s_barrier
	ds_read_b128 v[162:165], v156 offset:16384
	ds_read_b128 v[166:169], v156 offset:17408
	ds_read_b128 v[170:173], v156 offset:18432
	ds_read_b128 v[174:177], v156 offset:19456
	ds_read_b128 v[178:181], v156 offset:20480
	ds_read_b128 v[182:185], v156 offset:21504
	ds_read_b128 v[186:189], v156 offset:22528
	ds_read_b128 v[190:193], v156 offset:23552
	v_lshl_add_u64 v[212:213], s[0:1], 0, v[140:141]
	v_lshl_add_u64 v[210:211], s[30:31], 0, v[138:139]
	s_add_i32 s30, s75, s5
	s_mov_b32 m0, s30
	s_nop 0
	global_load_lds_dwordx4 v[210:211], off
	v_lshl_add_u64 v[214:215], v[210:211], 0, s[14:15]
	s_add_i32 m0, s30, 0x2000
	s_nop 0
	global_load_lds_dwordx4 v[214:215], off
	s_add_i32 s0, s76, s5
	v_lshl_add_u64 v[250:251], v[210:211], 0, s[16:17]
	s_mov_b32 m0, s0
	s_nop 0
	global_load_lds_dwordx4 v[250:251], off
	v_lshl_add_u64 v[250:251], v[210:211], 0, s[18:19]
	s_add_i32 m0, s0, 0x2000
	s_nop 0
	global_load_lds_dwordx4 v[250:251], off
	s_mov_b32 m0, s7
	s_nop 0
	global_load_lds_dwordx4 v[212:213], off
	v_lshl_add_u64 v[214:215], v[212:213], 0, s[14:15]
	s_mov_b32 m0, s24
	s_nop 0
	global_load_lds_dwordx4 v[214:215], off
	s_cmp_lg_u32 s98, 0
	s_cbranch_scc1 .Lsk2_p1
	s_waitcnt vmcnt(8)
	s_branch .Lsk3_p1

.Lsk3_p1:
	s_waitcnt lgkmcnt(0)
	s_barrier
	s_setprio 1
	v_mfma_f32_16x16x32_bf16 v[94:97], v[130:133], v[162:165], v[94:97]
	v_mfma_f32_16x16x32_bf16 v[90:93], v[148:151], v[162:165], v[90:93]
	v_mfma_f32_16x16x32_bf16 v[86:89], v[130:133], v[170:173], v[86:89]
	v_mfma_f32_16x16x32_bf16 v[82:85], v[148:151], v[170:173], v[82:85]
	v_mfma_f32_16x16x32_bf16 v[78:81], v[130:133], v[178:181], v[78:81]
	v_mfma_f32_16x16x32_bf16 v[74:77], v[148:151], v[178:181], v[74:77]
	v_mfma_f32_16x16x32_bf16 v[70:73], v[130:133], v[186:189], v[70:73]
	v_mfma_f32_16x16x32_bf16 v[66:69], v[148:151], v[186:189], v[66:69]
	v_mfma_f32_16x16x32_bf16 v[94:97], v[134:137], v[166:169], v[94:97]
	v_mfma_f32_16x16x32_bf16 v[90:93], v[158:161], v[166:169], v[90:93]
	v_mfma_f32_16x16x32_bf16 v[86:89], v[134:137], v[174:177], v[86:89]
	v_mfma_f32_16x16x32_bf16 v[82:85], v[158:161], v[174:177], v[82:85]
	v_mfma_f32_16x16x32_bf16 v[78:81], v[134:137], v[182:185], v[78:81]
	v_mfma_f32_16x16x32_bf16 v[74:77], v[158:161], v[182:185], v[74:77]
	v_mfma_f32_16x16x32_bf16 v[70:73], v[134:137], v[190:193], v[70:73]
	v_mfma_f32_16x16x32_bf16 v[66:69], v[158:161], v[190:193], v[66:69]
	v_mfma_f32_16x16x32_bf16 v[30:33], v[194:197], v[162:165], v[30:33]
	v_mfma_f32_16x16x32_bf16 v[26:29], v[202:205], v[162:165], v[26:29]
	v_mfma_f32_16x16x32_bf16 v[22:25], v[194:197], v[170:173], v[22:25]
	v_mfma_f32_16x16x32_bf16 v[18:21], v[202:205], v[170:173], v[18:21]
	v_mfma_f32_16x16x32_bf16 v[14:17], v[194:197], v[178:181], v[14:17]
	v_mfma_f32_16x16x32_bf16 v[10:13], v[202:205], v[178:181], v[10:13]
	v_mfma_f32_16x16x32_bf16 v[6:9], v[194:197], v[186:189], v[6:9]
	v_mfma_f32_16x16x32_bf16 v[2:5], v[202:205], v[186:189], v[2:5]
	v_mfma_f32_16x16x32_bf16 v[30:33], v[198:201], v[166:169], v[30:33]
	v_mfma_f32_16x16x32_bf16 v[26:29], v[206:209], v[166:169], v[26:29]
	v_mfma_f32_16x16x32_bf16 v[22:25], v[198:201], v[174:177], v[22:25]
	v_mfma_f32_16x16x32_bf16 v[18:21], v[206:209], v[174:177], v[18:21]
	v_mfma_f32_16x16x32_bf16 v[14:17], v[198:201], v[182:185], v[14:17]
	v_mfma_f32_16x16x32_bf16 v[10:13], v[206:209], v[182:185], v[10:13]
	v_mfma_f32_16x16x32_bf16 v[6:9], v[198:201], v[190:193], v[6:9]
	v_mfma_f32_16x16x32_bf16 v[2:5], v[206:209], v[190:193], v[2:5]
	s_setprio 0
	s_add_i32 s0, 0, 0x18000
	v_add_u32_e32 v158, s0, v154
	s_barrier
	s_add_i32 s1, 0, 0x1c000
	v_add_u32_e32 v206, s1, v154
	ds_read_b128 v[130:133], v158
	ds_read_b128 v[134:137], v158 offset:1024
	ds_read_b128 v[148:151], v158 offset:2048
	ds_read_b128 v[158:161], v158 offset:3072
	ds_read_b128 v[194:197], v206
	ds_read_b128 v[198:201], v206 offset:1024
	ds_read_b128 v[202:205], v206 offset:2048
	ds_read_b128 v[206:209], v206 offset:3072
	s_mov_b32 m0, s25
	v_lshl_add_u64 v[252:253], v[212:213], 0, s[16:17]
	ds_read_b128 v[162:165], v156 offset:32768
	ds_read_b128 v[166:169], v156 offset:33792
	ds_read_b128 v[170:173], v156 offset:34816
	ds_read_b128 v[174:177], v156 offset:35840
	ds_read_b128 v[178:181], v156 offset:36864
	ds_read_b128 v[182:185], v156 offset:37888
	ds_read_b128 v[186:189], v156 offset:38912
	ds_read_b128 v[190:193], v156 offset:39936
	global_load_lds_dwordx4 v[252:253], off
	v_lshl_add_u64 v[252:253], v[212:213], 0, s[18:19]
	s_mov_b32 m0, s26
	s_nop 0
	global_load_lds_dwordx4 v[252:253], off
	s_waitcnt vmcnt(8)
	s_waitcnt lgkmcnt(0)
	s_barrier
	s_setprio 1
	v_mfma_f32_16x16x32_bf16 v[126:129], v[130:133], v[162:165], v[126:129]
	v_mfma_f32_16x16x32_bf16 v[122:125], v[148:151], v[162:165], v[122:125]
	v_mfma_f32_16x16x32_bf16 v[118:121], v[130:133], v[170:173], v[118:121]
	v_mfma_f32_16x16x32_bf16 v[114:117], v[148:151], v[170:173], v[114:117]
	v_mfma_f32_16x16x32_bf16 v[110:113], v[130:133], v[178:181], v[110:113]
	v_mfma_f32_16x16x32_bf16 v[106:109], v[148:151], v[178:181], v[106:109]
	v_mfma_f32_16x16x32_bf16 v[102:105], v[130:133], v[186:189], v[102:105]
	v_mfma_f32_16x16x32_bf16 v[98:101], v[148:151], v[186:189], v[98:101]
	v_mfma_f32_16x16x32_bf16 v[126:129], v[134:137], v[166:169], v[126:129]
	v_mfma_f32_16x16x32_bf16 v[122:125], v[158:161], v[166:169], v[122:125]
	v_mfma_f32_16x16x32_bf16 v[118:121], v[134:137], v[174:177], v[118:121]
	v_mfma_f32_16x16x32_bf16 v[114:117], v[158:161], v[174:177], v[114:117]
	v_mfma_f32_16x16x32_bf16 v[110:113], v[134:137], v[182:185], v[110:113]
	v_mfma_f32_16x16x32_bf16 v[106:109], v[158:161], v[182:185], v[106:109]
	v_mfma_f32_16x16x32_bf16 v[102:105], v[134:137], v[190:193], v[102:105]
	v_mfma_f32_16x16x32_bf16 v[98:101], v[158:161], v[190:193], v[98:101]
	v_mfma_f32_16x16x32_bf16 v[62:65], v[194:197], v[162:165], v[62:65]
	v_mfma_f32_16x16x32_bf16 v[58:61], v[202:205], v[162:165], v[58:61]
	v_mfma_f32_16x16x32_bf16 v[54:57], v[194:197], v[170:173], v[54:57]
	v_mfma_f32_16x16x32_bf16 v[50:53], v[202:205], v[170:173], v[50:53]
	v_mfma_f32_16x16x32_bf16 v[46:49], v[194:197], v[178:181], v[46:49]
	v_mfma_f32_16x16x32_bf16 v[42:45], v[202:205], v[178:181], v[42:45]
	v_mfma_f32_16x16x32_bf16 v[38:41], v[194:197], v[186:189], v[38:41]
	v_mfma_f32_16x16x32_bf16 v[34:37], v[202:205], v[186:189], v[34:37]
	v_mfma_f32_16x16x32_bf16 v[62:65], v[198:201], v[166:169], v[62:65]
	v_mfma_f32_16x16x32_bf16 v[58:61], v[206:209], v[166:169], v[58:61]
	v_mfma_f32_16x16x32_bf16 v[54:57], v[198:201], v[174:177], v[54:57]
	v_mfma_f32_16x16x32_bf16 v[50:53], v[206:209], v[174:177], v[50:53]
	v_mfma_f32_16x16x32_bf16 v[46:49], v[198:201], v[182:185], v[46:49]
	v_mfma_f32_16x16x32_bf16 v[42:45], v[206:209], v[182:185], v[42:45]
	v_mfma_f32_16x16x32_bf16 v[38:41], v[198:201], v[190:193], v[38:41]
	v_mfma_f32_16x16x32_bf16 v[34:37], v[206:209], v[190:193], v[34:37]
	s_setprio 0
	s_barrier
	ds_read_b128 v[162:165], v156 offset:49152
	ds_read_b128 v[166:169], v156 offset:50176
	ds_read_b128 v[170:173], v156 offset:51200
	ds_read_b128 v[174:177], v156 offset:52224
	ds_read_b128 v[178:181], v156 offset:53248
	ds_read_b128 v[182:185], v156 offset:54272
	ds_read_b128 v[186:189], v156 offset:55296
	ds_read_b128 v[190:193], v156 offset:56320
	s_add_i32 s0, s0, s5
	v_lshl_add_u64 v[214:215], v[210:211], 0, s[38:39]
	s_mov_b32 m0, s0
	s_nop 0
	global_load_lds_dwordx4 v[214:215], off
	v_lshl_add_u64 v[214:215], v[210:211], 0, s[42:43]
	s_add_i32 m0, s0, 0x2000
	s_nop 0
	global_load_lds_dwordx4 v[214:215], off
	s_add_i32 s0, s1, s5
	v_lshl_add_u64 v[250:251], v[210:211], 0, s[44:45]
	s_mov_b32 m0, s0
	s_nop 0
	global_load_lds_dwordx4 v[250:251], off
	v_lshl_add_u64 v[250:251], v[210:211], 0, s[46:47]
	s_add_i32 m0, s0, 0x2000
	s_nop 0
	global_load_lds_dwordx4 v[250:251], off
	s_mov_b32 m0, s37
	v_lshl_add_u64 v[214:215], v[212:213], 0, s[38:39]
	global_load_lds_dwordx4 v[214:215], off
	v_lshl_add_u64 v[212:213], v[212:213], 0, s[42:43]
	s_mov_b32 m0, s40
	s_nop 0
	global_load_lds_dwordx4 v[212:213], off
	s_waitcnt vmcnt(8)
	s_waitcnt lgkmcnt(0)
	s_barrier
	s_setprio 1
	v_mfma_f32_16x16x32_bf16 v[94:97], v[130:133], v[162:165], v[94:97]
	v_mfma_f32_16x16x32_bf16 v[90:93], v[148:151], v[162:165], v[90:93]
	v_mfma_f32_16x16x32_bf16 v[86:89], v[130:133], v[170:173], v[86:89]
	v_mfma_f32_16x16x32_bf16 v[82:85], v[148:151], v[170:173], v[82:85]
	v_mfma_f32_16x16x32_bf16 v[78:81], v[130:133], v[178:181], v[78:81]
	v_mfma_f32_16x16x32_bf16 v[74:77], v[148:151], v[178:181], v[74:77]
	v_mfma_f32_16x16x32_bf16 v[70:73], v[130:133], v[186:189], v[70:73]
	v_mfma_f32_16x16x32_bf16 v[66:69], v[148:151], v[186:189], v[66:69]
	v_mfma_f32_16x16x32_bf16 v[94:97], v[134:137], v[166:169], v[94:97]
	v_mfma_f32_16x16x32_bf16 v[90:93], v[158:161], v[166:169], v[90:93]
	v_mfma_f32_16x16x32_bf16 v[86:89], v[134:137], v[174:177], v[86:89]
	v_mfma_f32_16x16x32_bf16 v[82:85], v[158:161], v[174:177], v[82:85]
	v_mfma_f32_16x16x32_bf16 v[78:81], v[134:137], v[182:185], v[78:81]
	v_mfma_f32_16x16x32_bf16 v[74:77], v[158:161], v[182:185], v[74:77]
	v_mfma_f32_16x16x32_bf16 v[70:73], v[134:137], v[190:193], v[70:73]
	v_mfma_f32_16x16x32_bf16 v[66:69], v[158:161], v[190:193], v[66:69]
	v_mfma_f32_16x16x32_bf16 v[30:33], v[194:197], v[162:165], v[30:33]
	v_mfma_f32_16x16x32_bf16 v[26:29], v[202:205], v[162:165], v[26:29]
	v_mfma_f32_16x16x32_bf16 v[22:25], v[194:197], v[170:173], v[22:25]
	v_mfma_f32_16x16x32_bf16 v[18:21], v[202:205], v[170:173], v[18:21]
	v_mfma_f32_16x16x32_bf16 v[14:17], v[194:197], v[178:181], v[14:17]
	v_mfma_f32_16x16x32_bf16 v[10:13], v[202:205], v[178:181], v[10:13]
	v_mfma_f32_16x16x32_bf16 v[6:9], v[194:197], v[186:189], v[6:9]
	v_mfma_f32_16x16x32_bf16 v[2:5], v[202:205], v[186:189], v[2:5]
	v_mfma_f32_16x16x32_bf16 v[30:33], v[198:201], v[166:169], v[30:33]
	v_mfma_f32_16x16x32_bf16 v[26:29], v[206:209], v[166:169], v[26:29]
	v_mfma_f32_16x16x32_bf16 v[22:25], v[198:201], v[174:177], v[22:25]
	v_mfma_f32_16x16x32_bf16 v[18:21], v[206:209], v[174:177], v[18:21]
	v_mfma_f32_16x16x32_bf16 v[14:17], v[198:201], v[182:185], v[14:17]
	v_mfma_f32_16x16x32_bf16 v[10:13], v[206:209], v[182:185], v[10:13]
	v_mfma_f32_16x16x32_bf16 v[6:9], v[198:201], v[190:193], v[6:9]
	v_mfma_f32_16x16x32_bf16 v[2:5], v[206:209], v[190:193], v[2:5]
	s_setprio 0
	s_add_i32 s68, s68, 2
	s_add_u32 s66, s66, 0x100
	s_addc_u32 s67, s67, 0
	s_add_u32 s64, s64, 0x100
	s_addc_u32 s65, s65, 0
	s_cmp_gt_u32 s68, 13
	s_barrier
	s_cbranch_scc0 .LBB0_190
	s_mov_b32 s98, 1
	s_and_b64 vcc, exec, s[48:49]
	s_cbranch_vccz .LBB0_193
	s_barrier

.LBB0_209:
	global_load_dword v17, v18, s[12:13] sc1
	global_load_dword v2, v18, s[14:15] sc1
	global_load_dword v3, v18, s[16:17] sc1
	global_load_dword v4, v18, s[18:19] sc1
	global_load_dword v5, v18, s[20:21] sc1
	global_load_dword v6, v18, s[22:23] sc1
	global_load_dword v7, v18, s[38:39] sc1
	global_load_dword v8, v18, s[42:43] sc1
	global_load_dword v9, v18, s[44:45] sc1
	global_load_dword v10, v18, s[46:47] sc1
	global_load_dword v11, v18, s[48:49] sc1
	global_load_dword v12, v18, s[50:51] sc1
	global_load_dword v13, v18, s[52:53] sc1
	global_load_dword v14, v18, s[54:55] sc1
	global_load_dword v15, v18, s[56:57] sc1
	global_load_dword v16, v18, s[58:59] sc1
	s_mov_b64 s[60:61], -1
	s_mov_b64 s[62:63], -1
	s_waitcnt vmcnt(14)
	v_add_u32_e32 v19, v2, v17
	s_waitcnt vmcnt(13)
	v_add_u32_e32 v19, v19, v3
	s_waitcnt vmcnt(12)
	v_add_u32_e32 v19, v19, v4
	s_waitcnt vmcnt(11)
	v_add_u32_e32 v19, v19, v5
	s_waitcnt vmcnt(10)
	v_add_u32_e32 v19, v19, v6
	s_waitcnt vmcnt(9)
	v_add_u32_e32 v19, v19, v7
	s_waitcnt vmcnt(8)
	v_add_u32_e32 v19, v19, v8
	s_waitcnt vmcnt(7)
	v_add_u32_e32 v19, v19, v9
	s_waitcnt vmcnt(6)
	v_add_u32_e32 v19, v19, v10
	s_waitcnt vmcnt(5)
	v_add_u32_e32 v19, v19, v11
	s_waitcnt vmcnt(4)
	v_add_u32_e32 v19, v19, v12
	s_waitcnt vmcnt(3)
	v_add_u32_e32 v19, v19, v13
	s_waitcnt vmcnt(2)
	v_add_u32_e32 v19, v19, v14
	s_waitcnt vmcnt(1)
	v_add_u32_e32 v19, v19, v15
	s_waitcnt vmcnt(0)
	v_add_u32_e32 v19, v19, v16
	v_cmp_eq_u32_e32 vcc, s0, v19
	s_cbranch_vccnz .LBB0_208
	s_and_b32 s3, s1, 0xff
	s_cmp_eq_u32 s3, 0
	s_mov_b64 s[64:65], -1
	s_cbranch_scc1 .LBB0_213
	s_and_b64 vcc, exec, s[64:65]
	s_cbranch_vccz .LBB0_208

.LBB0_227:
	s_and_b32 s1, s0, 0xff
	s_mov_b64 s[38:39], -1
	s_cmp_lg_u32 s1, 0
	s_mov_b64 s[44:45], -1
	s_cbranch_scc0 .LBB0_230
	s_and_b64 vcc, exec, s[44:45]
	s_cbranch_vccz .LBB0_226

.LBB0_244:
	s_and_b32 s1, s0, 0xff
	s_cmp_lg_u32 s1, 0
	s_mov_b64 s[42:43], -1
	s_cbranch_scc0 .LBB0_247
	s_mov_b64 s[44:45], -1
	s_and_b64 vcc, exec, s[42:43]
	s_cbranch_vccz .LBB0_243

.LBB0_329:
	global_load_dword v17, v18, s[14:15] sc1
	global_load_dword v2, v18, s[16:17] sc1
	global_load_dword v3, v18, s[18:19] sc1
	global_load_dword v4, v18, s[20:21] sc1
	global_load_dword v5, v18, s[22:23] sc1
	global_load_dword v6, v18, s[42:43] sc1
	global_load_dword v7, v18, s[44:45] sc1
	global_load_dword v8, v18, s[46:47] sc1
	global_load_dword v9, v18, s[48:49] sc1
	global_load_dword v10, v18, s[50:51] sc1
	global_load_dword v11, v18, s[52:53] sc1
	global_load_dword v12, v18, s[54:55] sc1
	global_load_dword v13, v18, s[56:57] sc1
	global_load_dword v14, v18, s[58:59] sc1
	global_load_dword v15, v18, s[60:61] sc1
	global_load_dword v16, v18, s[62:63] sc1
	s_mov_b64 s[64:65], -1
	s_mov_b64 s[66:67], -1
	s_waitcnt vmcnt(14)
	v_add_u32_e32 v19, v2, v17
	s_waitcnt vmcnt(13)
	v_add_u32_e32 v19, v19, v3
	s_waitcnt vmcnt(12)
	v_add_u32_e32 v19, v19, v4
	s_waitcnt vmcnt(11)
	v_add_u32_e32 v19, v19, v5
	s_waitcnt vmcnt(10)
	v_add_u32_e32 v19, v19, v6
	s_waitcnt vmcnt(9)
	v_add_u32_e32 v19, v19, v7
	s_waitcnt vmcnt(8)
	v_add_u32_e32 v19, v19, v8
	s_waitcnt vmcnt(7)
	v_add_u32_e32 v19, v19, v9
	s_waitcnt vmcnt(6)
	v_add_u32_e32 v19, v19, v10
	s_waitcnt vmcnt(5)
	v_add_u32_e32 v19, v19, v11
	s_waitcnt vmcnt(4)
	v_add_u32_e32 v19, v19, v12
	s_waitcnt vmcnt(3)
	v_add_u32_e32 v19, v19, v13
	s_waitcnt vmcnt(2)
	v_add_u32_e32 v19, v19, v14
	s_waitcnt vmcnt(1)
	v_add_u32_e32 v19, v19, v15
	s_waitcnt vmcnt(0)
	v_add_u32_e32 v19, v19, v16
	v_cmp_eq_u32_e32 vcc, s0, v19
	s_cbranch_vccnz .LBB0_328
	s_and_b32 s3, s1, 0xff
	s_cmp_eq_u32 s3, 0
	s_mov_b64 s[68:69], -1
	s_cbranch_scc1 .LBB0_333
	s_and_b64 vcc, exec, s[68:69]
	s_cbranch_vccz .LBB0_328

.LBB0_347:
	s_and_b32 s1, s0, 0xff
	s_mov_b64 s[44:45], -1
	s_cmp_lg_u32 s1, 0
	s_mov_b64 s[48:49], -1
	s_cbranch_scc0 .LBB0_350
	s_and_b64 vcc, exec, s[48:49]
	s_cbranch_vccz .LBB0_346

.LBB0_364:
	s_and_b32 s1, s0, 0xff
	s_cmp_lg_u32 s1, 0
	s_mov_b64 s[46:47], -1
	s_cbranch_scc0 .LBB0_367
	s_mov_b64 s[48:49], -1
	s_and_b64 vcc, exec, s[46:47]
	s_cbranch_vccz .LBB0_363

.LBB0_619:
	global_load_dword v17, v18, s[14:15] sc1
	s_waitcnt lgkmcnt(0)
	global_load_dword v2, v18, s[16:17] sc1
	global_load_dword v3, v18, s[18:19] sc1
	global_load_dword v4, v18, s[20:21] sc1
	global_load_dword v5, v18, s[22:23] sc1
	global_load_dword v6, v18, s[42:43] sc1
	global_load_dword v7, v18, s[44:45] sc1
	global_load_dword v8, v18, s[46:47] sc1
	global_load_dword v9, v18, s[48:49] sc1
	global_load_dword v10, v18, s[50:51] sc1
	global_load_dword v11, v18, s[52:53] sc1
	global_load_dword v12, v18, s[54:55] sc1
	global_load_dword v13, v18, s[56:57] sc1
	global_load_dword v14, v18, s[58:59] sc1
	global_load_dword v15, v18, s[60:61] sc1
	global_load_dword v16, v18, s[62:63] sc1
	s_mov_b64 s[64:65], -1
	s_mov_b64 s[66:67], -1
	s_waitcnt vmcnt(14)
	v_add_u32_e32 v19, v2, v17
	s_waitcnt vmcnt(13)
	v_add_u32_e32 v19, v19, v3
	s_waitcnt vmcnt(12)
	v_add_u32_e32 v19, v19, v4
	s_waitcnt vmcnt(11)
	v_add_u32_e32 v19, v19, v5
	s_waitcnt vmcnt(10)
	v_add_u32_e32 v19, v19, v6
	s_waitcnt vmcnt(9)
	v_add_u32_e32 v19, v19, v7
	s_waitcnt vmcnt(8)
	v_add_u32_e32 v19, v19, v8
	s_waitcnt vmcnt(7)
	v_add_u32_e32 v19, v19, v9
	s_waitcnt vmcnt(6)
	v_add_u32_e32 v19, v19, v10
	s_waitcnt vmcnt(5)
	v_add_u32_e32 v19, v19, v11
	s_waitcnt vmcnt(4)
	v_add_u32_e32 v19, v19, v12
	s_waitcnt vmcnt(3)
	v_add_u32_e32 v19, v19, v13
	s_waitcnt vmcnt(2)
	v_add_u32_e32 v19, v19, v14
	s_waitcnt vmcnt(1)
	v_add_u32_e32 v19, v19, v15
	s_waitcnt vmcnt(0)
	v_add_u32_e32 v19, v19, v16
	v_cmp_eq_u32_e32 vcc, s0, v19
	s_cbranch_vccnz .LBB0_618
	s_and_b32 s3, s1, 0xff
	s_cmp_eq_u32 s3, 0
	s_mov_b64 s[68:69], -1
	s_cbranch_scc1 .LBB0_623
	s_and_b64 vcc, exec, s[68:69]
	s_cbranch_vccz .LBB0_618

.LBB0_992:
	global_load_dword v17, v18, s[14:15] sc1
	s_waitcnt lgkmcnt(0)
	global_load_dword v2, v18, s[16:17] sc1
	global_load_dword v3, v18, s[18:19] sc1
	global_load_dword v4, v18, s[20:21] sc1
	global_load_dword v5, v18, s[22:23] sc1
	global_load_dword v6, v18, s[40:41] sc1
	global_load_dword v7, v18, s[42:43] sc1
	global_load_dword v8, v18, s[44:45] sc1
	global_load_dword v9, v18, s[46:47] sc1
	global_load_dword v10, v18, s[48:49] sc1
	global_load_dword v11, v18, s[50:51] sc1
	global_load_dword v12, v18, s[52:53] sc1
	global_load_dword v13, v18, s[54:55] sc1
	global_load_dword v14, v18, s[56:57] sc1
	global_load_dword v15, v18, s[58:59] sc1
	global_load_dword v16, v18, s[60:61] sc1
	s_mov_b64 s[62:63], -1
	s_mov_b64 s[64:65], -1
	s_waitcnt vmcnt(14)
	v_add_u32_e32 v19, v2, v17
	s_waitcnt vmcnt(13)
	v_add_u32_e32 v19, v19, v3
	s_waitcnt vmcnt(12)
	v_add_u32_e32 v19, v19, v4
	s_waitcnt vmcnt(11)
	v_add_u32_e32 v19, v19, v5
	s_waitcnt vmcnt(10)
	v_add_u32_e32 v19, v19, v6
	s_waitcnt vmcnt(9)
	v_add_u32_e32 v19, v19, v7
	s_waitcnt vmcnt(8)
	v_add_u32_e32 v19, v19, v8
	s_waitcnt vmcnt(7)
	v_add_u32_e32 v19, v19, v9
	s_waitcnt vmcnt(6)
	v_add_u32_e32 v19, v19, v10
	s_waitcnt vmcnt(5)
	v_add_u32_e32 v19, v19, v11
	s_waitcnt vmcnt(4)
	v_add_u32_e32 v19, v19, v12
	s_waitcnt vmcnt(3)
	v_add_u32_e32 v19, v19, v13
	s_waitcnt vmcnt(2)
	v_add_u32_e32 v19, v19, v14
	s_waitcnt vmcnt(1)
	v_add_u32_e32 v19, v19, v15
	s_waitcnt vmcnt(0)
	v_add_u32_e32 v19, v19, v16
	v_cmp_eq_u32_e32 vcc, s0, v19
	s_cbranch_vccnz .LBB0_991
	s_and_b32 s3, s1, 0xff
	s_cmp_eq_u32 s3, 0
	s_mov_b64 s[66:67], -1
	s_cbranch_scc1 .LBB0_996
	s_and_b64 vcc, exec, s[66:67]
	s_cbranch_vccz .LBB0_991

.LBB0_1010:
	s_and_b32 s1, s0, 0xff
	s_mov_b64 s[42:43], -1
	s_cmp_lg_u32 s1, 0
	s_mov_b64 s[46:47], -1
	s_cbranch_scc0 .LBB0_1013
	s_and_b64 vcc, exec, s[46:47]
	s_cbranch_vccz .LBB0_1009

.LBB0_1027:
	s_and_b32 s1, s0, 0xff
	s_cmp_lg_u32 s1, 0
	s_mov_b64 s[44:45], -1
	s_cbranch_scc0 .LBB0_1030
	s_mov_b64 s[46:47], -1
	s_and_b64 vcc, exec, s[44:45]
	s_cbranch_vccz .LBB0_1026

.Lsk1_p7:
	s_waitcnt lgkmcnt(0)
	s_barrier
	s_setprio 1
	v_mfma_f32_16x16x32_bf16 v[126:129], v[130:133], v[162:165], v[126:129]
	v_mfma_f32_16x16x32_bf16 v[122:125], v[148:151], v[162:165], v[122:125]
	v_mfma_f32_16x16x32_bf16 v[118:121], v[130:133], v[170:173], v[118:121]
	v_mfma_f32_16x16x32_bf16 v[114:117], v[148:151], v[170:173], v[114:117]
	v_mfma_f32_16x16x32_bf16 v[110:113], v[130:133], v[178:181], v[110:113]
	v_mfma_f32_16x16x32_bf16 v[106:109], v[148:151], v[178:181], v[106:109]
	v_mfma_f32_16x16x32_bf16 v[102:105], v[130:133], v[186:189], v[102:105]
	v_mfma_f32_16x16x32_bf16 v[98:101], v[148:151], v[186:189], v[98:101]
	v_mfma_f32_16x16x32_bf16 v[126:129], v[134:137], v[166:169], v[126:129]
	v_mfma_f32_16x16x32_bf16 v[122:125], v[158:161], v[166:169], v[122:125]
	v_mfma_f32_16x16x32_bf16 v[118:121], v[134:137], v[174:177], v[118:121]
	v_mfma_f32_16x16x32_bf16 v[114:117], v[158:161], v[174:177], v[114:117]
	v_mfma_f32_16x16x32_bf16 v[110:113], v[134:137], v[182:185], v[110:113]
	v_mfma_f32_16x16x32_bf16 v[106:109], v[158:161], v[182:185], v[106:109]
	v_mfma_f32_16x16x32_bf16 v[102:105], v[134:137], v[190:193], v[102:105]
	v_mfma_f32_16x16x32_bf16 v[98:101], v[158:161], v[190:193], v[98:101]
	v_mfma_f32_16x16x32_bf16 v[62:65], v[194:197], v[162:165], v[62:65]
	v_mfma_f32_16x16x32_bf16 v[58:61], v[202:205], v[162:165], v[58:61]
	v_mfma_f32_16x16x32_bf16 v[54:57], v[194:197], v[170:173], v[54:57]
	v_mfma_f32_16x16x32_bf16 v[50:53], v[202:205], v[170:173], v[50:53]
	v_mfma_f32_16x16x32_bf16 v[46:49], v[194:197], v[178:181], v[46:49]
	v_mfma_f32_16x16x32_bf16 v[42:45], v[202:205], v[178:181], v[42:45]
	v_mfma_f32_16x16x32_bf16 v[38:41], v[194:197], v[186:189], v[38:41]
	v_mfma_f32_16x16x32_bf16 v[34:37], v[202:205], v[186:189], v[34:37]
	v_mfma_f32_16x16x32_bf16 v[62:65], v[198:201], v[166:169], v[62:65]
	v_mfma_f32_16x16x32_bf16 v[58:61], v[206:209], v[166:169], v[58:61]
	v_mfma_f32_16x16x32_bf16 v[54:57], v[198:201], v[174:177], v[54:57]
	v_mfma_f32_16x16x32_bf16 v[50:53], v[206:209], v[174:177], v[50:53]
	v_mfma_f32_16x16x32_bf16 v[46:49], v[198:201], v[182:185], v[46:49]
	v_mfma_f32_16x16x32_bf16 v[42:45], v[206:209], v[182:185], v[42:45]
	v_mfma_f32_16x16x32_bf16 v[38:41], v[198:201], v[190:193], v[38:41]
	v_mfma_f32_16x16x32_bf16 v[34:37], v[206:209], v[190:193], v[34:37]
	s_setprio 0
	s_barrier
	ds_read_b128 v[162:165], v156 offset:16384
	ds_read_b128 v[166:169], v156 offset:17408
	ds_read_b128 v[170:173], v156 offset:18432
	ds_read_b128 v[174:177], v156 offset:19456
	ds_read_b128 v[178:181], v156 offset:20480
	ds_read_b128 v[182:185], v156 offset:21504
	ds_read_b128 v[186:189], v156 offset:22528
	ds_read_b128 v[190:193], v156 offset:23552
	v_lshl_add_u64 v[212:213], s[0:1], 0, v[140:141]
	v_lshl_add_u64 v[210:211], s[30:31], 0, v[138:139]
	s_add_i32 s30, s78, s7
	s_mov_b32 m0, s30
	s_nop 0
	global_load_lds_dwordx4 v[210:211], off
	v_lshl_add_u64 v[214:215], v[210:211], 0, s[14:15]
	s_add_i32 m0, s30, 0x2000
	s_nop 0
	global_load_lds_dwordx4 v[214:215], off
	s_add_i32 s0, s79, s7
	v_lshl_add_u64 v[250:251], v[210:211], 0, s[18:19]
	s_mov_b32 m0, s0
	s_nop 0
	global_load_lds_dwordx4 v[250:251], off
	v_lshl_add_u64 v[250:251], v[210:211], 0, s[20:21]
	s_add_i32 m0, s0, 0x2000
	s_nop 0
	global_load_lds_dwordx4 v[250:251], off
	s_mov_b32 m0, s9
	s_nop 0
	global_load_lds_dwordx4 v[212:213], off
	v_lshl_add_u64 v[214:215], v[212:213], 0, s[14:15]
	s_mov_b32 m0, s24
	s_nop 0
	global_load_lds_dwordx4 v[214:215], off
	s_cmp_lg_u32 s98, 0
	s_cbranch_scc1 .Lsk2_p7
	s_waitcnt vmcnt(8)
	s_branch .Lsk3_p7

.Lsk3_p7:
	s_waitcnt lgkmcnt(0)
	s_barrier
	s_setprio 1
	v_mfma_f32_16x16x32_bf16 v[94:97], v[130:133], v[162:165], v[94:97]
	v_mfma_f32_16x16x32_bf16 v[90:93], v[148:151], v[162:165], v[90:93]
	v_mfma_f32_16x16x32_bf16 v[86:89], v[130:133], v[170:173], v[86:89]
	v_mfma_f32_16x16x32_bf16 v[82:85], v[148:151], v[170:173], v[82:85]
	v_mfma_f32_16x16x32_bf16 v[78:81], v[130:133], v[178:181], v[78:81]
	v_mfma_f32_16x16x32_bf16 v[74:77], v[148:151], v[178:181], v[74:77]
	v_mfma_f32_16x16x32_bf16 v[70:73], v[130:133], v[186:189], v[70:73]
	v_mfma_f32_16x16x32_bf16 v[66:69], v[148:151], v[186:189], v[66:69]
	v_mfma_f32_16x16x32_bf16 v[94:97], v[134:137], v[166:169], v[94:97]
	v_mfma_f32_16x16x32_bf16 v[90:93], v[158:161], v[166:169], v[90:93]
	v_mfma_f32_16x16x32_bf16 v[86:89], v[134:137], v[174:177], v[86:89]
	v_mfma_f32_16x16x32_bf16 v[82:85], v[158:161], v[174:177], v[82:85]
	v_mfma_f32_16x16x32_bf16 v[78:81], v[134:137], v[182:185], v[78:81]
	v_mfma_f32_16x16x32_bf16 v[74:77], v[158:161], v[182:185], v[74:77]
	v_mfma_f32_16x16x32_bf16 v[70:73], v[134:137], v[190:193], v[70:73]
	v_mfma_f32_16x16x32_bf16 v[66:69], v[158:161], v[190:193], v[66:69]
	v_mfma_f32_16x16x32_bf16 v[30:33], v[194:197], v[162:165], v[30:33]
	v_mfma_f32_16x16x32_bf16 v[26:29], v[202:205], v[162:165], v[26:29]
	v_mfma_f32_16x16x32_bf16 v[22:25], v[194:197], v[170:173], v[22:25]
	v_mfma_f32_16x16x32_bf16 v[18:21], v[202:205], v[170:173], v[18:21]
	v_mfma_f32_16x16x32_bf16 v[14:17], v[194:197], v[178:181], v[14:17]
	v_mfma_f32_16x16x32_bf16 v[10:13], v[202:205], v[178:181], v[10:13]
	v_mfma_f32_16x16x32_bf16 v[6:9], v[194:197], v[186:189], v[6:9]
	v_mfma_f32_16x16x32_bf16 v[2:5], v[202:205], v[186:189], v[2:5]
	v_mfma_f32_16x16x32_bf16 v[30:33], v[198:201], v[166:169], v[30:33]
	v_mfma_f32_16x16x32_bf16 v[26:29], v[206:209], v[166:169], v[26:29]
	v_mfma_f32_16x16x32_bf16 v[22:25], v[198:201], v[174:177], v[22:25]
	v_mfma_f32_16x16x32_bf16 v[18:21], v[206:209], v[174:177], v[18:21]
	v_mfma_f32_16x16x32_bf16 v[14:17], v[198:201], v[182:185], v[14:17]
	v_mfma_f32_16x16x32_bf16 v[10:13], v[206:209], v[182:185], v[10:13]
	v_mfma_f32_16x16x32_bf16 v[6:9], v[198:201], v[190:193], v[6:9]
	v_mfma_f32_16x16x32_bf16 v[2:5], v[206:209], v[190:193], v[2:5]
	s_setprio 0
	s_add_i32 s0, 0, 0x18000
	v_add_u32_e32 v158, s0, v154
	s_barrier
	s_add_i32 s1, 0, 0x1c000
	v_add_u32_e32 v206, s1, v154
	ds_read_b128 v[130:133], v158
	ds_read_b128 v[134:137], v158 offset:1024
	ds_read_b128 v[148:151], v158 offset:2048
	ds_read_b128 v[158:161], v158 offset:3072
	ds_read_b128 v[194:197], v206
	ds_read_b128 v[198:201], v206 offset:1024
	ds_read_b128 v[202:205], v206 offset:2048
	ds_read_b128 v[206:209], v206 offset:3072
	s_mov_b32 m0, s25
	v_lshl_add_u64 v[252:253], v[212:213], 0, s[18:19]
	ds_read_b128 v[162:165], v156 offset:32768
	ds_read_b128 v[166:169], v156 offset:33792
	ds_read_b128 v[170:173], v156 offset:34816
	ds_read_b128 v[174:177], v156 offset:35840
	ds_read_b128 v[178:181], v156 offset:36864
	ds_read_b128 v[182:185], v156 offset:37888
	ds_read_b128 v[186:189], v156 offset:38912
	ds_read_b128 v[190:193], v156 offset:39936
	global_load_lds_dwordx4 v[252:253], off
	v_lshl_add_u64 v[252:253], v[212:213], 0, s[20:21]
	s_mov_b32 m0, s26
	s_nop 0
	global_load_lds_dwordx4 v[252:253], off
	s_waitcnt vmcnt(8)
	s_waitcnt lgkmcnt(0)
	s_barrier
	s_setprio 1
	v_mfma_f32_16x16x32_bf16 v[126:129], v[130:133], v[162:165], v[126:129]
	v_mfma_f32_16x16x32_bf16 v[122:125], v[148:151], v[162:165], v[122:125]
	v_mfma_f32_16x16x32_bf16 v[118:121], v[130:133], v[170:173], v[118:121]
	v_mfma_f32_16x16x32_bf16 v[114:117], v[148:151], v[170:173], v[114:117]
	v_mfma_f32_16x16x32_bf16 v[110:113], v[130:133], v[178:181], v[110:113]
	v_mfma_f32_16x16x32_bf16 v[106:109], v[148:151], v[178:181], v[106:109]
	v_mfma_f32_16x16x32_bf16 v[102:105], v[130:133], v[186:189], v[102:105]
	v_mfma_f32_16x16x32_bf16 v[98:101], v[148:151], v[186:189], v[98:101]
	v_mfma_f32_16x16x32_bf16 v[126:129], v[134:137], v[166:169], v[126:129]
	v_mfma_f32_16x16x32_bf16 v[122:125], v[158:161], v[166:169], v[122:125]
	v_mfma_f32_16x16x32_bf16 v[118:121], v[134:137], v[174:177], v[118:121]
	v_mfma_f32_16x16x32_bf16 v[114:117], v[158:161], v[174:177], v[114:117]
	v_mfma_f32_16x16x32_bf16 v[110:113], v[134:137], v[182:185], v[110:113]
	v_mfma_f32_16x16x32_bf16 v[106:109], v[158:161], v[182:185], v[106:109]
	v_mfma_f32_16x16x32_bf16 v[102:105], v[134:137], v[190:193], v[102:105]
	v_mfma_f32_16x16x32_bf16 v[98:101], v[158:161], v[190:193], v[98:101]
	v_mfma_f32_16x16x32_bf16 v[62:65], v[194:197], v[162:165], v[62:65]
	v_mfma_f32_16x16x32_bf16 v[58:61], v[202:205], v[162:165], v[58:61]
	v_mfma_f32_16x16x32_bf16 v[54:57], v[194:197], v[170:173], v[54:57]
	v_mfma_f32_16x16x32_bf16 v[50:53], v[202:205], v[170:173], v[50:53]
	v_mfma_f32_16x16x32_bf16 v[46:49], v[194:197], v[178:181], v[46:49]
	v_mfma_f32_16x16x32_bf16 v[42:45], v[202:205], v[178:181], v[42:45]
	v_mfma_f32_16x16x32_bf16 v[38:41], v[194:197], v[186:189], v[38:41]
	v_mfma_f32_16x16x32_bf16 v[34:37], v[202:205], v[186:189], v[34:37]
	v_mfma_f32_16x16x32_bf16 v[62:65], v[198:201], v[166:169], v[62:65]
	v_mfma_f32_16x16x32_bf16 v[58:61], v[206:209], v[166:169], v[58:61]
	v_mfma_f32_16x16x32_bf16 v[54:57], v[198:201], v[174:177], v[54:57]
	v_mfma_f32_16x16x32_bf16 v[50:53], v[206:209], v[174:177], v[50:53]
	v_mfma_f32_16x16x32_bf16 v[46:49], v[198:201], v[182:185], v[46:49]
	v_mfma_f32_16x16x32_bf16 v[42:45], v[206:209], v[182:185], v[42:45]
	v_mfma_f32_16x16x32_bf16 v[38:41], v[198:201], v[190:193], v[38:41]
	v_mfma_f32_16x16x32_bf16 v[34:37], v[206:209], v[190:193], v[34:37]
	s_setprio 0
	s_barrier
	ds_read_b128 v[162:165], v156 offset:49152
	ds_read_b128 v[166:169], v156 offset:50176
	ds_read_b128 v[170:173], v156 offset:51200
	ds_read_b128 v[174:177], v156 offset:52224
	ds_read_b128 v[178:181], v156 offset:53248
	ds_read_b128 v[182:185], v156 offset:54272
	ds_read_b128 v[186:189], v156 offset:55296
	ds_read_b128 v[190:193], v156 offset:56320
	s_add_i32 s0, s0, s7
	v_lshl_add_u64 v[214:215], v[210:211], 0, s[42:43]
	s_mov_b32 m0, s0
	s_nop 0
	global_load_lds_dwordx4 v[214:215], off
	v_lshl_add_u64 v[214:215], v[210:211], 0, s[44:45]
	s_add_i32 m0, s0, 0x2000
	s_nop 0
	global_load_lds_dwordx4 v[214:215], off
	s_add_i32 s0, s1, s7
	v_lshl_add_u64 v[250:251], v[210:211], 0, s[46:47]
	s_mov_b32 m0, s0
	s_nop 0
	global_load_lds_dwordx4 v[250:251], off
	v_lshl_add_u64 v[250:251], v[210:211], 0, s[48:49]
	s_add_i32 m0, s0, 0x2000
	s_nop 0
	global_load_lds_dwordx4 v[250:251], off
	s_mov_b32 m0, s72
	v_lshl_add_u64 v[214:215], v[212:213], 0, s[42:43]
	global_load_lds_dwordx4 v[214:215], off
	v_lshl_add_u64 v[212:213], v[212:213], 0, s[44:45]
	s_mov_b32 m0, s73
	s_nop 0
	global_load_lds_dwordx4 v[212:213], off
	s_waitcnt vmcnt(8)
	s_waitcnt lgkmcnt(0)
	s_barrier
	s_setprio 1
	v_mfma_f32_16x16x32_bf16 v[94:97], v[130:133], v[162:165], v[94:97]
	v_mfma_f32_16x16x32_bf16 v[90:93], v[148:151], v[162:165], v[90:93]
	v_mfma_f32_16x16x32_bf16 v[86:89], v[130:133], v[170:173], v[86:89]
	v_mfma_f32_16x16x32_bf16 v[82:85], v[148:151], v[170:173], v[82:85]
	v_mfma_f32_16x16x32_bf16 v[78:81], v[130:133], v[178:181], v[78:81]
	v_mfma_f32_16x16x32_bf16 v[74:77], v[148:151], v[178:181], v[74:77]
	v_mfma_f32_16x16x32_bf16 v[70:73], v[130:133], v[186:189], v[70:73]
	v_mfma_f32_16x16x32_bf16 v[66:69], v[148:151], v[186:189], v[66:69]
	v_mfma_f32_16x16x32_bf16 v[94:97], v[134:137], v[166:169], v[94:97]
	v_mfma_f32_16x16x32_bf16 v[90:93], v[158:161], v[166:169], v[90:93]
	v_mfma_f32_16x16x32_bf16 v[86:89], v[134:137], v[174:177], v[86:89]
	v_mfma_f32_16x16x32_bf16 v[82:85], v[158:161], v[174:177], v[82:85]
	v_mfma_f32_16x16x32_bf16 v[78:81], v[134:137], v[182:185], v[78:81]
	v_mfma_f32_16x16x32_bf16 v[74:77], v[158:161], v[182:185], v[74:77]
	v_mfma_f32_16x16x32_bf16 v[70:73], v[134:137], v[190:193], v[70:73]
	v_mfma_f32_16x16x32_bf16 v[66:69], v[158:161], v[190:193], v[66:69]
	v_mfma_f32_16x16x32_bf16 v[30:33], v[194:197], v[162:165], v[30:33]
	v_mfma_f32_16x16x32_bf16 v[26:29], v[202:205], v[162:165], v[26:29]
	v_mfma_f32_16x16x32_bf16 v[22:25], v[194:197], v[170:173], v[22:25]
	v_mfma_f32_16x16x32_bf16 v[18:21], v[202:205], v[170:173], v[18:21]
	v_mfma_f32_16x16x32_bf16 v[14:17], v[194:197], v[178:181], v[14:17]
	v_mfma_f32_16x16x32_bf16 v[10:13], v[202:205], v[178:181], v[10:13]
	v_mfma_f32_16x16x32_bf16 v[6:9], v[194:197], v[186:189], v[6:9]
	v_mfma_f32_16x16x32_bf16 v[2:5], v[202:205], v[186:189], v[2:5]
	v_mfma_f32_16x16x32_bf16 v[30:33], v[198:201], v[166:169], v[30:33]
	v_mfma_f32_16x16x32_bf16 v[26:29], v[206:209], v[166:169], v[26:29]
	v_mfma_f32_16x16x32_bf16 v[22:25], v[198:201], v[174:177], v[22:25]
	v_mfma_f32_16x16x32_bf16 v[18:21], v[206:209], v[174:177], v[18:21]
	v_mfma_f32_16x16x32_bf16 v[14:17], v[198:201], v[182:185], v[14:17]
	v_mfma_f32_16x16x32_bf16 v[10:13], v[206:209], v[182:185], v[10:13]
	v_mfma_f32_16x16x32_bf16 v[6:9], v[198:201], v[190:193], v[6:9]
	v_mfma_f32_16x16x32_bf16 v[2:5], v[206:209], v[190:193], v[2:5]
	s_setprio 0
	s_add_i32 s69, s69, 2
	s_add_u32 s38, s38, 0x100
	s_addc_u32 s68, s68, 0
	s_add_u32 s66, s66, 0x100
	s_addc_u32 s67, s67, 0
	s_cmp_gt_u32 s69, 13
	s_barrier
	s_cbranch_scc0 .LBB0_1049
	s_mov_b32 s98, 1
	s_and_b64 vcc, exec, s[50:51]
	s_cbranch_vccz .LBB0_1052
	s_barrier

.LBB0_1068:
	global_load_dword v17, v18, s[14:15] sc1
	s_waitcnt lgkmcnt(0)
	global_load_dword v2, v18, s[18:19] sc1
	global_load_dword v3, v18, s[20:21] sc1
	global_load_dword v4, v18, s[22:23] sc1
	global_load_dword v5, v18, s[40:41] sc1
	global_load_dword v6, v18, s[42:43] sc1
	global_load_dword v7, v18, s[44:45] sc1
	global_load_dword v8, v18, s[46:47] sc1
	global_load_dword v9, v18, s[48:49] sc1
	global_load_dword v10, v18, s[50:51] sc1
	global_load_dword v11, v18, s[52:53] sc1
	global_load_dword v12, v18, s[54:55] sc1
	global_load_dword v13, v18, s[56:57] sc1
	global_load_dword v14, v18, s[58:59] sc1
	global_load_dword v15, v18, s[60:61] sc1
	global_load_dword v16, v18, s[62:63] sc1
	s_mov_b64 s[64:65], -1
	s_mov_b64 s[66:67], -1
	s_waitcnt vmcnt(14)
	v_add_u32_e32 v19, v2, v17
	s_waitcnt vmcnt(13)
	v_add_u32_e32 v19, v19, v3
	s_waitcnt vmcnt(12)
	v_add_u32_e32 v19, v19, v4
	s_waitcnt vmcnt(11)
	v_add_u32_e32 v19, v19, v5
	s_waitcnt vmcnt(10)
	v_add_u32_e32 v19, v19, v6
	s_waitcnt vmcnt(9)
	v_add_u32_e32 v19, v19, v7
	s_waitcnt vmcnt(8)
	v_add_u32_e32 v19, v19, v8
	s_waitcnt vmcnt(7)
	v_add_u32_e32 v19, v19, v9
	s_waitcnt vmcnt(6)
	v_add_u32_e32 v19, v19, v10
	s_waitcnt vmcnt(5)
	v_add_u32_e32 v19, v19, v11
	s_waitcnt vmcnt(4)
	v_add_u32_e32 v19, v19, v12
	s_waitcnt vmcnt(3)
	v_add_u32_e32 v19, v19, v13
	s_waitcnt vmcnt(2)
	v_add_u32_e32 v19, v19, v14
	s_waitcnt vmcnt(1)
	v_add_u32_e32 v19, v19, v15
	s_waitcnt vmcnt(0)
	v_add_u32_e32 v19, v19, v16
	v_cmp_eq_u32_e32 vcc, s0, v19
	s_cbranch_vccnz .LBB0_1067
	s_and_b32 s3, s1, 0xff
	s_cmp_eq_u32 s3, 0
	s_mov_b64 s[68:69], -1
	s_cbranch_scc1 .LBB0_1072
	s_and_b64 vcc, exec, s[68:69]
	s_cbranch_vccz .LBB0_1067

.LBB0_1177:
	global_load_dword v17, v18, s[14:15] sc1
	s_waitcnt lgkmcnt(0)
	global_load_dword v2, v18, s[18:19] sc1
	global_load_dword v3, v18, s[20:21] sc1
	global_load_dword v4, v18, s[22:23] sc1
	global_load_dword v5, v18, s[38:39] sc1
	global_load_dword v6, v18, s[40:41] sc1
	global_load_dword v7, v18, s[42:43] sc1
	global_load_dword v8, v18, s[44:45] sc1
	global_load_dword v9, v18, s[46:47] sc1
	global_load_dword v10, v18, s[48:49] sc1
	global_load_dword v11, v18, s[50:51] sc1
	global_load_dword v12, v18, s[52:53] sc1
	global_load_dword v13, v18, s[54:55] sc1
	global_load_dword v14, v18, s[56:57] sc1
	global_load_dword v15, v18, s[58:59] sc1
	global_load_dword v16, v18, s[60:61] sc1
	s_mov_b64 s[62:63], -1
	s_mov_b64 s[64:65], -1
	s_waitcnt vmcnt(14)
	v_add_u32_e32 v19, v2, v17
	s_waitcnt vmcnt(13)
	v_add_u32_e32 v19, v19, v3
	s_waitcnt vmcnt(12)
	v_add_u32_e32 v19, v19, v4
	s_waitcnt vmcnt(11)
	v_add_u32_e32 v19, v19, v5
	s_waitcnt vmcnt(10)
	v_add_u32_e32 v19, v19, v6
	s_waitcnt vmcnt(9)
	v_add_u32_e32 v19, v19, v7
	s_waitcnt vmcnt(8)
	v_add_u32_e32 v19, v19, v8
	s_waitcnt vmcnt(7)
	v_add_u32_e32 v19, v19, v9
	s_waitcnt vmcnt(6)
	v_add_u32_e32 v19, v19, v10
	s_waitcnt vmcnt(5)
	v_add_u32_e32 v19, v19, v11
	s_waitcnt vmcnt(4)
	v_add_u32_e32 v19, v19, v12
	s_waitcnt vmcnt(3)
	v_add_u32_e32 v19, v19, v13
	s_waitcnt vmcnt(2)
	v_add_u32_e32 v19, v19, v14
	s_waitcnt vmcnt(1)
	v_add_u32_e32 v19, v19, v15
	s_waitcnt vmcnt(0)
	v_add_u32_e32 v19, v19, v16
	v_cmp_eq_u32_e32 vcc, s0, v19
	s_cbranch_vccnz .LBB0_1176
	s_and_b32 s3, s1, 0xff
	s_cmp_eq_u32 s3, 0
	s_mov_b64 s[66:67], -1
	s_cbranch_scc1 .LBB0_1181
	s_and_b64 vcc, exec, s[66:67]
	s_cbranch_vccz .LBB0_1176

.LBB0_1507:
	global_load_dword v17, v18, s[14:15] sc1
	s_waitcnt lgkmcnt(0)
	global_load_dword v2, v18, s[16:17] sc1
	global_load_dword v3, v18, s[18:19] sc1
	global_load_dword v4, v18, s[20:21] sc1
	global_load_dword v5, v18, s[22:23] sc1
	global_load_dword v6, v18, s[36:37] sc1
	global_load_dword v7, v18, s[38:39] sc1
	global_load_dword v8, v18, s[40:41] sc1
	global_load_dword v9, v18, s[42:43] sc1
	global_load_dword v10, v18, s[44:45] sc1
	global_load_dword v11, v18, s[46:47] sc1
	global_load_dword v12, v18, s[48:49] sc1
	global_load_dword v13, v18, s[50:51] sc1
	global_load_dword v14, v18, s[52:53] sc1
	global_load_dword v15, v18, s[54:55] sc1
	global_load_dword v16, v18, s[56:57] sc1
	s_mov_b64 s[58:59], -1
	s_mov_b64 s[60:61], -1
	s_waitcnt vmcnt(14)
	v_add_u32_e32 v19, v2, v17
	s_waitcnt vmcnt(13)
	v_add_u32_e32 v19, v19, v3
	s_waitcnt vmcnt(12)
	v_add_u32_e32 v19, v19, v4
	s_waitcnt vmcnt(11)
	v_add_u32_e32 v19, v19, v5
	s_waitcnt vmcnt(10)
	v_add_u32_e32 v19, v19, v6
	s_waitcnt vmcnt(9)
	v_add_u32_e32 v19, v19, v7
	s_waitcnt vmcnt(8)
	v_add_u32_e32 v19, v19, v8
	s_waitcnt vmcnt(7)
	v_add_u32_e32 v19, v19, v9
	s_waitcnt vmcnt(6)
	v_add_u32_e32 v19, v19, v10
	s_waitcnt vmcnt(5)
	v_add_u32_e32 v19, v19, v11
	s_waitcnt vmcnt(4)
	v_add_u32_e32 v19, v19, v12
	s_waitcnt vmcnt(3)
	v_add_u32_e32 v19, v19, v13
	s_waitcnt vmcnt(2)
	v_add_u32_e32 v19, v19, v14
	s_waitcnt vmcnt(1)
	v_add_u32_e32 v19, v19, v15
	s_waitcnt vmcnt(0)
	v_add_u32_e32 v19, v19, v16
	v_cmp_eq_u32_e32 vcc, s0, v19
	s_cbranch_vccnz .LBB0_1506
	s_and_b32 s3, s1, 0xff
	s_cmp_eq_u32 s3, 0
	s_mov_b64 s[62:63], -1
	s_cbranch_scc1 .LBB0_1511
	s_and_b64 vcc, exec, s[62:63]
	s_cbranch_vccz .LBB0_1506

.LBB0_1525:
	s_and_b32 s1, s0, 0xff
	s_mov_b64 s[38:39], -1
	s_cmp_lg_u32 s1, 0
	s_mov_b64 s[42:43], -1
	s_cbranch_scc0 .LBB0_1528
	s_and_b64 vcc, exec, s[42:43]
	s_cbranch_vccz .LBB0_1524

.LBB0_1542:
	s_and_b32 s1, s0, 0xff
	s_cmp_lg_u32 s1, 0
	s_mov_b64 s[40:41], -1
	s_cbranch_scc0 .LBB0_1545
	s_mov_b64 s[42:43], -1
	s_and_b64 vcc, exec, s[40:41]
	s_cbranch_vccz .LBB0_1541

.LBB0_1574:
	global_load_dword v17, v18, s[14:15] sc1
	s_waitcnt lgkmcnt(0)
	global_load_dword v2, v18, s[16:17] sc1
	global_load_dword v3, v18, s[18:19] sc1
	global_load_dword v4, v18, s[20:21] sc1
	global_load_dword v5, v18, s[22:23] sc1
	global_load_dword v6, v18, s[34:35] sc1
	global_load_dword v7, v18, s[36:37] sc1
	global_load_dword v8, v18, s[38:39] sc1
	global_load_dword v9, v18, s[40:41] sc1
	global_load_dword v10, v18, s[42:43] sc1
	global_load_dword v11, v18, s[44:45] sc1
	global_load_dword v12, v18, s[46:47] sc1
	global_load_dword v13, v18, s[48:49] sc1
	global_load_dword v14, v18, s[50:51] sc1
	global_load_dword v15, v18, s[52:53] sc1
	global_load_dword v16, v18, s[54:55] sc1
	s_mov_b64 s[56:57], -1
	s_mov_b64 s[58:59], -1
	s_waitcnt vmcnt(14)
	v_add_u32_e32 v19, v2, v17
	s_waitcnt vmcnt(13)
	v_add_u32_e32 v19, v19, v3
	s_waitcnt vmcnt(12)
	v_add_u32_e32 v19, v19, v4
	s_waitcnt vmcnt(11)
	v_add_u32_e32 v19, v19, v5
	s_waitcnt vmcnt(10)
	v_add_u32_e32 v19, v19, v6
	s_waitcnt vmcnt(9)
	v_add_u32_e32 v19, v19, v7
	s_waitcnt vmcnt(8)
	v_add_u32_e32 v19, v19, v8
	s_waitcnt vmcnt(7)
	v_add_u32_e32 v19, v19, v9
	s_waitcnt vmcnt(6)
	v_add_u32_e32 v19, v19, v10
	s_waitcnt vmcnt(5)
	v_add_u32_e32 v19, v19, v11
	s_waitcnt vmcnt(4)
	v_add_u32_e32 v19, v19, v12
	s_waitcnt vmcnt(3)
	v_add_u32_e32 v19, v19, v13
	s_waitcnt vmcnt(2)
	v_add_u32_e32 v19, v19, v14
	s_waitcnt vmcnt(1)
	v_add_u32_e32 v19, v19, v15
	s_waitcnt vmcnt(0)
	v_add_u32_e32 v19, v19, v16
	v_cmp_eq_u32_e32 vcc, s0, v19
	s_cbranch_vccnz .LBB0_1573
	s_and_b32 s3, s1, 0xff
	s_cmp_eq_u32 s3, 0
	s_mov_b64 s[60:61], -1
	s_cbranch_scc1 .LBB0_1578
	s_and_b64 vcc, exec, s[60:61]
	s_cbranch_vccz .LBB0_1573

.LBB0_1592:
	s_and_b32 s1, s0, 0xff
	s_mov_b64 s[36:37], -1
	s_cmp_lg_u32 s1, 0
	s_mov_b64 s[40:41], -1
	s_cbranch_scc0 .LBB0_1595
	s_and_b64 vcc, exec, s[40:41]
	s_cbranch_vccz .LBB0_1591

.LBB0_1609:
	s_and_b32 s1, s0, 0xff
	s_cmp_lg_u32 s1, 0
	s_mov_b64 s[38:39], -1
	s_cbranch_scc0 .LBB0_1612
	s_mov_b64 s[40:41], -1
	s_and_b64 vcc, exec, s[38:39]
	s_cbranch_vccz .LBB0_1608

.Lsk1_p13:
	s_waitcnt lgkmcnt(0)
	s_barrier
	s_setprio 1
	v_mfma_f32_16x16x32_bf16 v[130:133], v[122:125], v[146:149], v[130:133]
	v_mfma_f32_16x16x32_bf16 v[126:129], v[138:141], v[146:149], v[126:129]
	v_mfma_f32_16x16x32_bf16 v[118:121], v[122:125], v[154:157], v[118:121]
	v_mfma_f32_16x16x32_bf16 v[114:117], v[138:141], v[154:157], v[114:117]
	v_mfma_f32_16x16x32_bf16 v[110:113], v[122:125], v[168:171], v[110:113]
	v_mfma_f32_16x16x32_bf16 v[106:109], v[138:141], v[168:171], v[106:109]
	v_mfma_f32_16x16x32_bf16 v[102:105], v[122:125], v[176:179], v[102:105]
	v_mfma_f32_16x16x32_bf16 v[98:101], v[138:141], v[176:179], v[98:101]
	v_mfma_f32_16x16x32_bf16 v[130:133], v[134:137], v[150:153], v[130:133]
	v_mfma_f32_16x16x32_bf16 v[126:129], v[142:145], v[150:153], v[126:129]
	v_mfma_f32_16x16x32_bf16 v[118:121], v[134:137], v[158:161], v[118:121]
	v_mfma_f32_16x16x32_bf16 v[114:117], v[142:145], v[158:161], v[114:117]
	v_mfma_f32_16x16x32_bf16 v[110:113], v[134:137], v[172:175], v[110:113]
	v_mfma_f32_16x16x32_bf16 v[106:109], v[142:145], v[172:175], v[106:109]
	v_mfma_f32_16x16x32_bf16 v[102:105], v[134:137], v[180:183], v[102:105]
	v_mfma_f32_16x16x32_bf16 v[98:101], v[142:145], v[180:183], v[98:101]
	v_mfma_f32_16x16x32_bf16 v[62:65], v[192:195], v[146:149], v[62:65]
	v_mfma_f32_16x16x32_bf16 v[58:61], v[200:203], v[146:149], v[58:61]
	v_mfma_f32_16x16x32_bf16 v[54:57], v[192:195], v[154:157], v[54:57]
	v_mfma_f32_16x16x32_bf16 v[50:53], v[200:203], v[154:157], v[50:53]
	v_mfma_f32_16x16x32_bf16 v[46:49], v[192:195], v[168:171], v[46:49]
	v_mfma_f32_16x16x32_bf16 v[42:45], v[200:203], v[168:171], v[42:45]
	v_mfma_f32_16x16x32_bf16 v[38:41], v[192:195], v[176:179], v[38:41]
	v_mfma_f32_16x16x32_bf16 v[34:37], v[200:203], v[176:179], v[34:37]
	v_mfma_f32_16x16x32_bf16 v[62:65], v[196:199], v[150:153], v[62:65]
	v_mfma_f32_16x16x32_bf16 v[58:61], v[204:207], v[150:153], v[58:61]
	v_mfma_f32_16x16x32_bf16 v[54:57], v[196:199], v[158:161], v[54:57]
	v_mfma_f32_16x16x32_bf16 v[50:53], v[204:207], v[158:161], v[50:53]
	v_mfma_f32_16x16x32_bf16 v[46:49], v[196:199], v[172:175], v[46:49]
	v_mfma_f32_16x16x32_bf16 v[42:45], v[204:207], v[172:175], v[42:45]
	v_mfma_f32_16x16x32_bf16 v[38:41], v[196:199], v[180:183], v[38:41]
	v_mfma_f32_16x16x32_bf16 v[34:37], v[204:207], v[180:183], v[34:37]
	s_setprio 0
	s_barrier
	ds_read_b128 v[146:149], v190 offset:16384
	ds_read_b128 v[150:153], v190 offset:17408
	ds_read_b128 v[154:157], v190 offset:18432
	ds_read_b128 v[158:161], v190 offset:19456
	ds_read_b128 v[168:171], v190 offset:20480
	ds_read_b128 v[172:175], v190 offset:21504
	ds_read_b128 v[176:179], v190 offset:22528
	ds_read_b128 v[180:183], v190 offset:23552
	v_lshl_add_u64 v[208:209], s[0:1], 0, v[164:165]
	v_lshl_add_u64 v[184:185], s[30:31], 0, v[162:163]
	s_add_i32 s30, s72, s5
	s_mov_b32 m0, s30
	s_nop 0
	global_load_lds_dwordx4 v[184:185], off
	v_lshl_add_u64 v[210:211], v[184:185], 0, s[12:13]
	s_add_i32 m0, s30, 0x2000
	s_nop 0
	global_load_lds_dwordx4 v[210:211], off
	s_add_i32 s0, s73, s5
	v_lshl_add_u64 v[250:251], v[184:185], 0, s[14:15]
	s_mov_b32 m0, s0
	s_nop 0
	global_load_lds_dwordx4 v[250:251], off
	v_lshl_add_u64 v[250:251], v[184:185], 0, s[16:17]
	s_add_i32 m0, s0, 0x2000
	s_nop 0
	global_load_lds_dwordx4 v[250:251], off
	s_mov_b32 m0, s6
	s_nop 0
	global_load_lds_dwordx4 v[208:209], off
	v_lshl_add_u64 v[210:211], v[208:209], 0, s[12:13]
	s_mov_b32 m0, s7
	s_nop 0
	global_load_lds_dwordx4 v[210:211], off
	s_cmp_lg_u32 s98, 0
	s_cbranch_scc1 .Lsk2_p13
	s_waitcnt vmcnt(8)
	s_branch .Lsk3_p13

.Lsk3_p13:
	s_waitcnt lgkmcnt(0)
	s_barrier
	s_setprio 1
	v_mfma_f32_16x16x32_bf16 v[94:97], v[122:125], v[146:149], v[94:97]
	v_mfma_f32_16x16x32_bf16 v[90:93], v[138:141], v[146:149], v[90:93]
	v_mfma_f32_16x16x32_bf16 v[86:89], v[122:125], v[154:157], v[86:89]
	v_mfma_f32_16x16x32_bf16 v[82:85], v[138:141], v[154:157], v[82:85]
	v_mfma_f32_16x16x32_bf16 v[78:81], v[122:125], v[168:171], v[78:81]
	v_mfma_f32_16x16x32_bf16 v[74:77], v[138:141], v[168:171], v[74:77]
	v_mfma_f32_16x16x32_bf16 v[70:73], v[122:125], v[176:179], v[70:73]
	v_mfma_f32_16x16x32_bf16 v[66:69], v[138:141], v[176:179], v[66:69]
	v_mfma_f32_16x16x32_bf16 v[94:97], v[134:137], v[150:153], v[94:97]
	v_mfma_f32_16x16x32_bf16 v[90:93], v[142:145], v[150:153], v[90:93]
	v_mfma_f32_16x16x32_bf16 v[86:89], v[134:137], v[158:161], v[86:89]
	v_mfma_f32_16x16x32_bf16 v[82:85], v[142:145], v[158:161], v[82:85]
	v_mfma_f32_16x16x32_bf16 v[78:81], v[134:137], v[172:175], v[78:81]
	v_mfma_f32_16x16x32_bf16 v[74:77], v[142:145], v[172:175], v[74:77]
	v_mfma_f32_16x16x32_bf16 v[70:73], v[134:137], v[180:183], v[70:73]
	v_mfma_f32_16x16x32_bf16 v[66:69], v[142:145], v[180:183], v[66:69]
	v_mfma_f32_16x16x32_bf16 v[30:33], v[192:195], v[146:149], v[30:33]
	v_mfma_f32_16x16x32_bf16 v[26:29], v[200:203], v[146:149], v[26:29]
	v_mfma_f32_16x16x32_bf16 v[22:25], v[192:195], v[154:157], v[22:25]
	v_mfma_f32_16x16x32_bf16 v[18:21], v[200:203], v[154:157], v[18:21]
	v_mfma_f32_16x16x32_bf16 v[14:17], v[192:195], v[168:171], v[14:17]
	v_mfma_f32_16x16x32_bf16 v[10:13], v[200:203], v[168:171], v[10:13]
	v_mfma_f32_16x16x32_bf16 v[6:9], v[192:195], v[176:179], v[6:9]
	v_mfma_f32_16x16x32_bf16 v[2:5], v[200:203], v[176:179], v[2:5]
	v_mfma_f32_16x16x32_bf16 v[30:33], v[196:199], v[150:153], v[30:33]
	v_mfma_f32_16x16x32_bf16 v[26:29], v[204:207], v[150:153], v[26:29]
	v_mfma_f32_16x16x32_bf16 v[22:25], v[196:199], v[158:161], v[22:25]
	v_mfma_f32_16x16x32_bf16 v[18:21], v[204:207], v[158:161], v[18:21]
	v_mfma_f32_16x16x32_bf16 v[14:17], v[196:199], v[172:175], v[14:17]
	v_mfma_f32_16x16x32_bf16 v[10:13], v[204:207], v[172:175], v[10:13]
	v_mfma_f32_16x16x32_bf16 v[6:9], v[196:199], v[180:183], v[6:9]
	v_mfma_f32_16x16x32_bf16 v[2:5], v[204:207], v[180:183], v[2:5]
	s_setprio 0
	s_add_i32 s0, 0, 0x18000
	v_add_u32_e32 v142, s0, v188
	s_barrier
	s_add_i32 s1, 0, 0x1c000
	v_add_u32_e32 v204, s1, v188
	ds_read_b128 v[122:125], v142
	ds_read_b128 v[134:137], v142 offset:1024
	ds_read_b128 v[138:141], v142 offset:2048
	ds_read_b128 v[142:145], v142 offset:3072
	ds_read_b128 v[192:195], v204
	ds_read_b128 v[196:199], v204 offset:1024
	ds_read_b128 v[200:203], v204 offset:2048
	ds_read_b128 v[204:207], v204 offset:3072
	s_mov_b32 m0, s24
	v_lshl_add_u64 v[252:253], v[208:209], 0, s[14:15]
	ds_read_b128 v[146:149], v190 offset:32768
	ds_read_b128 v[150:153], v190 offset:33792
	ds_read_b128 v[154:157], v190 offset:34816
	ds_read_b128 v[158:161], v190 offset:35840
	ds_read_b128 v[168:171], v190 offset:36864
	ds_read_b128 v[172:175], v190 offset:37888
	ds_read_b128 v[176:179], v190 offset:38912
	ds_read_b128 v[180:183], v190 offset:39936
	global_load_lds_dwordx4 v[252:253], off
	v_lshl_add_u64 v[252:253], v[208:209], 0, s[16:17]
	s_mov_b32 m0, s25
	s_nop 0
	global_load_lds_dwordx4 v[252:253], off
	s_waitcnt vmcnt(8)
	s_waitcnt lgkmcnt(0)
	s_barrier
	s_setprio 1
	v_mfma_f32_16x16x32_bf16 v[130:133], v[122:125], v[146:149], v[130:133]
	v_mfma_f32_16x16x32_bf16 v[126:129], v[138:141], v[146:149], v[126:129]
	v_mfma_f32_16x16x32_bf16 v[118:121], v[122:125], v[154:157], v[118:121]
	v_mfma_f32_16x16x32_bf16 v[114:117], v[138:141], v[154:157], v[114:117]
	v_mfma_f32_16x16x32_bf16 v[110:113], v[122:125], v[168:171], v[110:113]
	v_mfma_f32_16x16x32_bf16 v[106:109], v[138:141], v[168:171], v[106:109]
	v_mfma_f32_16x16x32_bf16 v[102:105], v[122:125], v[176:179], v[102:105]
	v_mfma_f32_16x16x32_bf16 v[98:101], v[138:141], v[176:179], v[98:101]
	v_mfma_f32_16x16x32_bf16 v[130:133], v[134:137], v[150:153], v[130:133]
	v_mfma_f32_16x16x32_bf16 v[126:129], v[142:145], v[150:153], v[126:129]
	v_mfma_f32_16x16x32_bf16 v[118:121], v[134:137], v[158:161], v[118:121]
	v_mfma_f32_16x16x32_bf16 v[114:117], v[142:145], v[158:161], v[114:117]
	v_mfma_f32_16x16x32_bf16 v[110:113], v[134:137], v[172:175], v[110:113]
	v_mfma_f32_16x16x32_bf16 v[106:109], v[142:145], v[172:175], v[106:109]
	v_mfma_f32_16x16x32_bf16 v[102:105], v[134:137], v[180:183], v[102:105]
	v_mfma_f32_16x16x32_bf16 v[98:101], v[142:145], v[180:183], v[98:101]
	v_mfma_f32_16x16x32_bf16 v[62:65], v[192:195], v[146:149], v[62:65]
	v_mfma_f32_16x16x32_bf16 v[58:61], v[200:203], v[146:149], v[58:61]
	v_mfma_f32_16x16x32_bf16 v[54:57], v[192:195], v[154:157], v[54:57]
	v_mfma_f32_16x16x32_bf16 v[50:53], v[200:203], v[154:157], v[50:53]
	v_mfma_f32_16x16x32_bf16 v[46:49], v[192:195], v[168:171], v[46:49]
	v_mfma_f32_16x16x32_bf16 v[42:45], v[200:203], v[168:171], v[42:45]
	v_mfma_f32_16x16x32_bf16 v[38:41], v[192:195], v[176:179], v[38:41]
	v_mfma_f32_16x16x32_bf16 v[34:37], v[200:203], v[176:179], v[34:37]
	v_mfma_f32_16x16x32_bf16 v[62:65], v[196:199], v[150:153], v[62:65]
	v_mfma_f32_16x16x32_bf16 v[58:61], v[204:207], v[150:153], v[58:61]
	v_mfma_f32_16x16x32_bf16 v[54:57], v[196:199], v[158:161], v[54:57]
	v_mfma_f32_16x16x32_bf16 v[50:53], v[204:207], v[158:161], v[50:53]
	v_mfma_f32_16x16x32_bf16 v[46:49], v[196:199], v[172:175], v[46:49]
	v_mfma_f32_16x16x32_bf16 v[42:45], v[204:207], v[172:175], v[42:45]
	v_mfma_f32_16x16x32_bf16 v[38:41], v[196:199], v[180:183], v[38:41]
	v_mfma_f32_16x16x32_bf16 v[34:37], v[204:207], v[180:183], v[34:37]
	s_setprio 0
	s_barrier
	ds_read_b128 v[146:149], v190 offset:49152
	ds_read_b128 v[150:153], v190 offset:50176
	ds_read_b128 v[154:157], v190 offset:51200
	ds_read_b128 v[158:161], v190 offset:52224
	ds_read_b128 v[168:171], v190 offset:53248
	ds_read_b128 v[172:175], v190 offset:54272
	ds_read_b128 v[176:179], v190 offset:55296
	ds_read_b128 v[180:183], v190 offset:56320
	s_add_i32 s0, s0, s5
	v_lshl_add_u64 v[210:211], v[184:185], 0, s[22:23]
	s_mov_b32 m0, s0
	s_nop 0
	global_load_lds_dwordx4 v[210:211], off
	v_lshl_add_u64 v[210:211], v[184:185], 0, s[34:35]
	s_add_i32 m0, s0, 0x2000
	s_nop 0
	global_load_lds_dwordx4 v[210:211], off
	s_add_i32 s0, s1, s5
	v_lshl_add_u64 v[250:251], v[184:185], 0, s[36:37]
	s_mov_b32 m0, s0
	s_nop 0
	global_load_lds_dwordx4 v[250:251], off
	v_lshl_add_u64 v[250:251], v[184:185], 0, s[38:39]
	s_add_i32 m0, s0, 0x2000
	s_nop 0
	global_load_lds_dwordx4 v[250:251], off
	s_mov_b32 m0, s66
	v_lshl_add_u64 v[210:211], v[208:209], 0, s[22:23]
	global_load_lds_dwordx4 v[210:211], off
	v_lshl_add_u64 v[208:209], v[208:209], 0, s[34:35]
	s_mov_b32 m0, s67
	s_nop 0
	global_load_lds_dwordx4 v[208:209], off
	s_waitcnt vmcnt(8)
	s_waitcnt lgkmcnt(0)
	s_barrier
	s_setprio 1
	v_mfma_f32_16x16x32_bf16 v[94:97], v[122:125], v[146:149], v[94:97]
	v_mfma_f32_16x16x32_bf16 v[90:93], v[138:141], v[146:149], v[90:93]
	v_mfma_f32_16x16x32_bf16 v[86:89], v[122:125], v[154:157], v[86:89]
	v_mfma_f32_16x16x32_bf16 v[82:85], v[138:141], v[154:157], v[82:85]
	v_mfma_f32_16x16x32_bf16 v[78:81], v[122:125], v[168:171], v[78:81]
	v_mfma_f32_16x16x32_bf16 v[74:77], v[138:141], v[168:171], v[74:77]
	v_mfma_f32_16x16x32_bf16 v[70:73], v[122:125], v[176:179], v[70:73]
	v_mfma_f32_16x16x32_bf16 v[66:69], v[138:141], v[176:179], v[66:69]
	v_mfma_f32_16x16x32_bf16 v[94:97], v[134:137], v[150:153], v[94:97]
	v_mfma_f32_16x16x32_bf16 v[90:93], v[142:145], v[150:153], v[90:93]
	v_mfma_f32_16x16x32_bf16 v[86:89], v[134:137], v[158:161], v[86:89]
	v_mfma_f32_16x16x32_bf16 v[82:85], v[142:145], v[158:161], v[82:85]
	v_mfma_f32_16x16x32_bf16 v[78:81], v[134:137], v[172:175], v[78:81]
	v_mfma_f32_16x16x32_bf16 v[74:77], v[142:145], v[172:175], v[74:77]
	v_mfma_f32_16x16x32_bf16 v[70:73], v[134:137], v[180:183], v[70:73]
	v_mfma_f32_16x16x32_bf16 v[66:69], v[142:145], v[180:183], v[66:69]
	v_mfma_f32_16x16x32_bf16 v[30:33], v[192:195], v[146:149], v[30:33]
	v_mfma_f32_16x16x32_bf16 v[26:29], v[200:203], v[146:149], v[26:29]
	v_mfma_f32_16x16x32_bf16 v[22:25], v[192:195], v[154:157], v[22:25]
	v_mfma_f32_16x16x32_bf16 v[18:21], v[200:203], v[154:157], v[18:21]
	v_mfma_f32_16x16x32_bf16 v[14:17], v[192:195], v[168:171], v[14:17]
	v_mfma_f32_16x16x32_bf16 v[10:13], v[200:203], v[168:171], v[10:13]
	v_mfma_f32_16x16x32_bf16 v[6:9], v[192:195], v[176:179], v[6:9]
	v_mfma_f32_16x16x32_bf16 v[2:5], v[200:203], v[176:179], v[2:5]
	v_mfma_f32_16x16x32_bf16 v[30:33], v[196:199], v[150:153], v[30:33]
	v_mfma_f32_16x16x32_bf16 v[26:29], v[204:207], v[150:153], v[26:29]
	v_mfma_f32_16x16x32_bf16 v[22:25], v[196:199], v[158:161], v[22:25]
	v_mfma_f32_16x16x32_bf16 v[18:21], v[204:207], v[158:161], v[18:21]
	v_mfma_f32_16x16x32_bf16 v[14:17], v[196:199], v[172:175], v[14:17]
	v_mfma_f32_16x16x32_bf16 v[10:13], v[204:207], v[172:175], v[10:13]
	v_mfma_f32_16x16x32_bf16 v[6:9], v[196:199], v[180:183], v[6:9]
	v_mfma_f32_16x16x32_bf16 v[2:5], v[204:207], v[180:183], v[2:5]
	s_setprio 0
	s_add_i32 s79, s79, 2
	s_add_u32 s62, s62, 0x100
	s_addc_u32 s63, s63, 0
	s_add_u32 s60, s60, 0x100
	s_addc_u32 s61, s61, 0
	s_cmp_gt_u32 s79, 13
	s_barrier
	s_cbranch_scc0 .LBB0_1631
	s_mov_b32 s98, 1
	s_and_b64 vcc, exec, s[40:41]
	s_cbranch_vccz .LBB0_1634
	s_barrier

.LBB0_1642:
	global_load_dword v17, v18, s[12:13] sc1
	s_waitcnt lgkmcnt(0)
	global_load_dword v2, v18, s[14:15] sc1
	global_load_dword v3, v18, s[16:17] sc1
	global_load_dword v4, v18, s[18:19] sc1
	global_load_dword v5, v18, s[20:21] sc1
	global_load_dword v6, v18, s[22:23] sc1
	global_load_dword v7, v18, s[34:35] sc1
	global_load_dword v8, v18, s[36:37] sc1
	global_load_dword v9, v18, s[38:39] sc1
	global_load_dword v10, v18, s[40:41] sc1
	global_load_dword v11, v18, s[42:43] sc1
	global_load_dword v12, v18, s[44:45] sc1
	global_load_dword v13, v18, s[46:47] sc1
	global_load_dword v14, v18, s[48:49] sc1
	global_load_dword v15, v18, s[50:51] sc1
	global_load_dword v16, v18, s[52:53] sc1
	s_mov_b64 s[54:55], -1
	s_mov_b64 s[56:57], -1
	s_waitcnt vmcnt(14)
	v_add_u32_e32 v19, v2, v17
	s_waitcnt vmcnt(13)
	v_add_u32_e32 v19, v19, v3
	s_waitcnt vmcnt(12)
	v_add_u32_e32 v19, v19, v4
	s_waitcnt vmcnt(11)
	v_add_u32_e32 v19, v19, v5
	s_waitcnt vmcnt(10)
	v_add_u32_e32 v19, v19, v6
	s_waitcnt vmcnt(9)
	v_add_u32_e32 v19, v19, v7
	s_waitcnt vmcnt(8)
	v_add_u32_e32 v19, v19, v8
	s_waitcnt vmcnt(7)
	v_add_u32_e32 v19, v19, v9
	s_waitcnt vmcnt(6)
	v_add_u32_e32 v19, v19, v10
	s_waitcnt vmcnt(5)
	v_add_u32_e32 v19, v19, v11
	s_waitcnt vmcnt(4)
	v_add_u32_e32 v19, v19, v12
	s_waitcnt vmcnt(3)
	v_add_u32_e32 v19, v19, v13
	s_waitcnt vmcnt(2)
	v_add_u32_e32 v19, v19, v14
	s_waitcnt vmcnt(1)
	v_add_u32_e32 v19, v19, v15
	s_waitcnt vmcnt(0)
	v_add_u32_e32 v19, v19, v16
	v_cmp_eq_u32_e32 vcc, s0, v19
	s_cbranch_vccnz .LBB0_1641
	s_and_b32 s3, s1, 0xff
	s_cmp_eq_u32 s3, 0
	s_mov_b64 s[58:59], -1
	s_cbranch_scc1 .LBB0_1646
	s_and_b64 vcc, exec, s[58:59]
	s_cbranch_vccz .LBB0_1641

.LBB0_1660:
	s_and_b32 s1, s0, 0xff
	s_mov_b64 s[34:35], -1
	s_cmp_lg_u32 s1, 0
	s_mov_b64 s[38:39], -1
	s_cbranch_scc0 .LBB0_1663
	s_and_b64 vcc, exec, s[38:39]
	s_cbranch_vccz .LBB0_1659

.LBB0_1677:
	s_and_b32 s1, s0, 0xff
	s_cmp_lg_u32 s1, 0
	s_mov_b64 s[36:37], -1
	s_cbranch_scc0 .LBB0_1680
	s_mov_b64 s[38:39], -1
	s_and_b64 vcc, exec, s[36:37]
	s_cbranch_vccz .LBB0_1676

.Lsk1_p14:
	s_waitcnt lgkmcnt(0)
	s_barrier
	s_setprio 1
	v_mfma_f32_16x16x32_bf16 v[126:129], v[130:133], v[146:149], v[126:129]
	v_mfma_f32_16x16x32_bf16 v[122:125], v[138:141], v[146:149], v[122:125]
	v_mfma_f32_16x16x32_bf16 v[118:121], v[130:133], v[154:157], v[118:121]
	v_mfma_f32_16x16x32_bf16 v[114:117], v[138:141], v[154:157], v[114:117]
	v_mfma_f32_16x16x32_bf16 v[110:113], v[130:133], v[162:165], v[110:113]
	v_mfma_f32_16x16x32_bf16 v[106:109], v[138:141], v[162:165], v[106:109]
	v_mfma_f32_16x16x32_bf16 v[102:105], v[130:133], v[170:173], v[102:105]
	v_mfma_f32_16x16x32_bf16 v[98:101], v[138:141], v[170:173], v[98:101]
	v_mfma_f32_16x16x32_bf16 v[126:129], v[134:137], v[150:153], v[126:129]
	v_mfma_f32_16x16x32_bf16 v[122:125], v[142:145], v[150:153], v[122:125]
	v_mfma_f32_16x16x32_bf16 v[118:121], v[134:137], v[158:161], v[118:121]
	v_mfma_f32_16x16x32_bf16 v[114:117], v[142:145], v[158:161], v[114:117]
	v_mfma_f32_16x16x32_bf16 v[110:113], v[134:137], v[166:169], v[110:113]
	v_mfma_f32_16x16x32_bf16 v[106:109], v[142:145], v[166:169], v[106:109]
	v_mfma_f32_16x16x32_bf16 v[102:105], v[134:137], v[174:177], v[102:105]
	v_mfma_f32_16x16x32_bf16 v[98:101], v[142:145], v[174:177], v[98:101]
	v_mfma_f32_16x16x32_bf16 v[62:65], v[178:181], v[146:149], v[62:65]
	v_mfma_f32_16x16x32_bf16 v[58:61], v[186:189], v[146:149], v[58:61]
	v_mfma_f32_16x16x32_bf16 v[54:57], v[178:181], v[154:157], v[54:57]
	v_mfma_f32_16x16x32_bf16 v[50:53], v[186:189], v[154:157], v[50:53]
	v_mfma_f32_16x16x32_bf16 v[46:49], v[178:181], v[162:165], v[46:49]
	v_mfma_f32_16x16x32_bf16 v[42:45], v[186:189], v[162:165], v[42:45]
	v_mfma_f32_16x16x32_bf16 v[38:41], v[178:181], v[170:173], v[38:41]
	v_mfma_f32_16x16x32_bf16 v[34:37], v[186:189], v[170:173], v[34:37]
	v_mfma_f32_16x16x32_bf16 v[62:65], v[182:185], v[150:153], v[62:65]
	v_mfma_f32_16x16x32_bf16 v[58:61], v[190:193], v[150:153], v[58:61]
	v_mfma_f32_16x16x32_bf16 v[54:57], v[182:185], v[158:161], v[54:57]
	v_mfma_f32_16x16x32_bf16 v[50:53], v[190:193], v[158:161], v[50:53]
	v_mfma_f32_16x16x32_bf16 v[46:49], v[182:185], v[166:169], v[46:49]
	v_mfma_f32_16x16x32_bf16 v[42:45], v[190:193], v[166:169], v[42:45]
	v_mfma_f32_16x16x32_bf16 v[38:41], v[182:185], v[174:177], v[38:41]
	v_mfma_f32_16x16x32_bf16 v[34:37], v[190:193], v[174:177], v[34:37]
	s_setprio 0
	s_barrier
	ds_read_b128 v[146:149], v214 offset:16384
	ds_read_b128 v[150:153], v214 offset:17408
	ds_read_b128 v[154:157], v214 offset:18432
	ds_read_b128 v[158:161], v214 offset:19456
	ds_read_b128 v[162:165], v214 offset:20480
	ds_read_b128 v[166:169], v214 offset:21504
	ds_read_b128 v[170:173], v214 offset:22528
	ds_read_b128 v[174:177], v214 offset:23552
	v_lshl_add_u64 v[202:203], s[0:1], 0, v[194:195]
	v_lshl_add_u64 v[200:201], s[30:31], 0, v[196:197]
	s_add_i32 s30, s73, s5
	s_mov_b32 m0, s30
	s_nop 0
	global_load_lds_dwordx4 v[200:201], off
	v_lshl_add_u64 v[204:205], v[200:201], 0, s[10:11]
	s_add_i32 m0, s30, 0x2000
	s_nop 0
	global_load_lds_dwordx4 v[204:205], off
	s_add_i32 s0, s74, s5
	v_lshl_add_u64 v[250:251], v[200:201], 0, s[16:17]
	s_mov_b32 m0, s0
	s_nop 0
	global_load_lds_dwordx4 v[250:251], off
	v_lshl_add_u64 v[250:251], v[200:201], 0, s[18:19]
	s_add_i32 m0, s0, 0x2000
	s_nop 0
	global_load_lds_dwordx4 v[250:251], off
	s_mov_b32 m0, s6
	s_nop 0
	global_load_lds_dwordx4 v[202:203], off
	v_lshl_add_u64 v[204:205], v[202:203], 0, s[10:11]
	s_mov_b32 m0, s7
	s_nop 0
	global_load_lds_dwordx4 v[204:205], off
	s_cmp_lg_u32 s98, 0
	s_cbranch_scc1 .Lsk2_p14
	s_waitcnt vmcnt(8)
	s_branch .Lsk3_p14

.Lsk3_p14:
	s_waitcnt lgkmcnt(0)
	s_barrier
	s_setprio 1
	v_mfma_f32_16x16x32_bf16 v[94:97], v[130:133], v[146:149], v[94:97]
	v_mfma_f32_16x16x32_bf16 v[90:93], v[138:141], v[146:149], v[90:93]
	v_mfma_f32_16x16x32_bf16 v[86:89], v[130:133], v[154:157], v[86:89]
	v_mfma_f32_16x16x32_bf16 v[82:85], v[138:141], v[154:157], v[82:85]
	v_mfma_f32_16x16x32_bf16 v[78:81], v[130:133], v[162:165], v[78:81]
	v_mfma_f32_16x16x32_bf16 v[74:77], v[138:141], v[162:165], v[74:77]
	v_mfma_f32_16x16x32_bf16 v[70:73], v[130:133], v[170:173], v[70:73]
	v_mfma_f32_16x16x32_bf16 v[66:69], v[138:141], v[170:173], v[66:69]
	v_mfma_f32_16x16x32_bf16 v[94:97], v[134:137], v[150:153], v[94:97]
	v_mfma_f32_16x16x32_bf16 v[90:93], v[142:145], v[150:153], v[90:93]
	v_mfma_f32_16x16x32_bf16 v[86:89], v[134:137], v[158:161], v[86:89]
	v_mfma_f32_16x16x32_bf16 v[82:85], v[142:145], v[158:161], v[82:85]
	v_mfma_f32_16x16x32_bf16 v[78:81], v[134:137], v[166:169], v[78:81]
	v_mfma_f32_16x16x32_bf16 v[74:77], v[142:145], v[166:169], v[74:77]
	v_mfma_f32_16x16x32_bf16 v[70:73], v[134:137], v[174:177], v[70:73]
	v_mfma_f32_16x16x32_bf16 v[66:69], v[142:145], v[174:177], v[66:69]
	v_mfma_f32_16x16x32_bf16 v[30:33], v[178:181], v[146:149], v[30:33]
	v_mfma_f32_16x16x32_bf16 v[26:29], v[186:189], v[146:149], v[26:29]
	v_mfma_f32_16x16x32_bf16 v[22:25], v[178:181], v[154:157], v[22:25]
	v_mfma_f32_16x16x32_bf16 v[18:21], v[186:189], v[154:157], v[18:21]
	v_mfma_f32_16x16x32_bf16 v[14:17], v[178:181], v[162:165], v[14:17]
	v_mfma_f32_16x16x32_bf16 v[10:13], v[186:189], v[162:165], v[10:13]
	v_mfma_f32_16x16x32_bf16 v[6:9], v[178:181], v[170:173], v[6:9]
	v_mfma_f32_16x16x32_bf16 v[2:5], v[186:189], v[170:173], v[2:5]
	v_mfma_f32_16x16x32_bf16 v[30:33], v[182:185], v[150:153], v[30:33]
	v_mfma_f32_16x16x32_bf16 v[26:29], v[190:193], v[150:153], v[26:29]
	v_mfma_f32_16x16x32_bf16 v[22:25], v[182:185], v[158:161], v[22:25]
	v_mfma_f32_16x16x32_bf16 v[18:21], v[190:193], v[158:161], v[18:21]
	v_mfma_f32_16x16x32_bf16 v[14:17], v[182:185], v[166:169], v[14:17]
	v_mfma_f32_16x16x32_bf16 v[10:13], v[190:193], v[166:169], v[10:13]
	v_mfma_f32_16x16x32_bf16 v[6:9], v[182:185], v[174:177], v[6:9]
	v_mfma_f32_16x16x32_bf16 v[2:5], v[190:193], v[174:177], v[2:5]
	s_setprio 0
	s_add_i32 s0, 0, 0x18000
	v_add_u32_e32 v142, s0, v212
	s_barrier
	s_add_i32 s1, 0, 0x1c000
	v_add_u32_e32 v190, s1, v212
	ds_read_b128 v[130:133], v142
	ds_read_b128 v[134:137], v142 offset:1024
	ds_read_b128 v[138:141], v142 offset:2048
	ds_read_b128 v[142:145], v142 offset:3072
	ds_read_b128 v[178:181], v190
	ds_read_b128 v[182:185], v190 offset:1024
	ds_read_b128 v[186:189], v190 offset:2048
	ds_read_b128 v[190:193], v190 offset:3072
	s_mov_b32 m0, s24
	v_lshl_add_u64 v[252:253], v[202:203], 0, s[16:17]
	ds_read_b128 v[146:149], v214 offset:32768
	ds_read_b128 v[150:153], v214 offset:33792
	ds_read_b128 v[154:157], v214 offset:34816
	ds_read_b128 v[158:161], v214 offset:35840
	ds_read_b128 v[162:165], v214 offset:36864
	ds_read_b128 v[166:169], v214 offset:37888
	ds_read_b128 v[170:173], v214 offset:38912
	ds_read_b128 v[174:177], v214 offset:39936
	global_load_lds_dwordx4 v[252:253], off
	v_lshl_add_u64 v[252:253], v[202:203], 0, s[18:19]
	s_mov_b32 m0, s25
	s_nop 0
	global_load_lds_dwordx4 v[252:253], off
	s_waitcnt vmcnt(8)
	s_waitcnt lgkmcnt(0)
	s_barrier
	s_setprio 1
	v_mfma_f32_16x16x32_bf16 v[126:129], v[130:133], v[146:149], v[126:129]
	v_mfma_f32_16x16x32_bf16 v[122:125], v[138:141], v[146:149], v[122:125]
	v_mfma_f32_16x16x32_bf16 v[118:121], v[130:133], v[154:157], v[118:121]
	v_mfma_f32_16x16x32_bf16 v[114:117], v[138:141], v[154:157], v[114:117]
	v_mfma_f32_16x16x32_bf16 v[110:113], v[130:133], v[162:165], v[110:113]
	v_mfma_f32_16x16x32_bf16 v[106:109], v[138:141], v[162:165], v[106:109]
	v_mfma_f32_16x16x32_bf16 v[102:105], v[130:133], v[170:173], v[102:105]
	v_mfma_f32_16x16x32_bf16 v[98:101], v[138:141], v[170:173], v[98:101]
	v_mfma_f32_16x16x32_bf16 v[126:129], v[134:137], v[150:153], v[126:129]
	v_mfma_f32_16x16x32_bf16 v[122:125], v[142:145], v[150:153], v[122:125]
	v_mfma_f32_16x16x32_bf16 v[118:121], v[134:137], v[158:161], v[118:121]
	v_mfma_f32_16x16x32_bf16 v[114:117], v[142:145], v[158:161], v[114:117]
	v_mfma_f32_16x16x32_bf16 v[110:113], v[134:137], v[166:169], v[110:113]
	v_mfma_f32_16x16x32_bf16 v[106:109], v[142:145], v[166:169], v[106:109]
	v_mfma_f32_16x16x32_bf16 v[102:105], v[134:137], v[174:177], v[102:105]
	v_mfma_f32_16x16x32_bf16 v[98:101], v[142:145], v[174:177], v[98:101]
	v_mfma_f32_16x16x32_bf16 v[62:65], v[178:181], v[146:149], v[62:65]
	v_mfma_f32_16x16x32_bf16 v[58:61], v[186:189], v[146:149], v[58:61]
	v_mfma_f32_16x16x32_bf16 v[54:57], v[178:181], v[154:157], v[54:57]
	v_mfma_f32_16x16x32_bf16 v[50:53], v[186:189], v[154:157], v[50:53]
	v_mfma_f32_16x16x32_bf16 v[46:49], v[178:181], v[162:165], v[46:49]
	v_mfma_f32_16x16x32_bf16 v[42:45], v[186:189], v[162:165], v[42:45]
	v_mfma_f32_16x16x32_bf16 v[38:41], v[178:181], v[170:173], v[38:41]
	v_mfma_f32_16x16x32_bf16 v[34:37], v[186:189], v[170:173], v[34:37]
	v_mfma_f32_16x16x32_bf16 v[62:65], v[182:185], v[150:153], v[62:65]
	v_mfma_f32_16x16x32_bf16 v[58:61], v[190:193], v[150:153], v[58:61]
	v_mfma_f32_16x16x32_bf16 v[54:57], v[182:185], v[158:161], v[54:57]
	v_mfma_f32_16x16x32_bf16 v[50:53], v[190:193], v[158:161], v[50:53]
	v_mfma_f32_16x16x32_bf16 v[46:49], v[182:185], v[166:169], v[46:49]
	v_mfma_f32_16x16x32_bf16 v[42:45], v[190:193], v[166:169], v[42:45]
	v_mfma_f32_16x16x32_bf16 v[38:41], v[182:185], v[174:177], v[38:41]
	v_mfma_f32_16x16x32_bf16 v[34:37], v[190:193], v[174:177], v[34:37]
	s_setprio 0
	s_barrier
	ds_read_b128 v[146:149], v214 offset:49152
	ds_read_b128 v[150:153], v214 offset:50176
	ds_read_b128 v[154:157], v214 offset:51200
	ds_read_b128 v[158:161], v214 offset:52224
	ds_read_b128 v[162:165], v214 offset:53248
	ds_read_b128 v[166:169], v214 offset:54272
	ds_read_b128 v[170:173], v214 offset:55296
	ds_read_b128 v[174:177], v214 offset:56320
	s_add_i32 s0, s0, s5
	v_lshl_add_u64 v[204:205], v[200:201], 0, s[38:39]
	s_mov_b32 m0, s0
	s_nop 0
	global_load_lds_dwordx4 v[204:205], off
	v_lshl_add_u64 v[204:205], v[200:201], 0, s[40:41]
	s_add_i32 m0, s0, 0x2000
	s_nop 0
	global_load_lds_dwordx4 v[204:205], off
	s_add_i32 s0, s1, s5
	v_lshl_add_u64 v[250:251], v[200:201], 0, s[42:43]
	s_mov_b32 m0, s0
	s_nop 0
	global_load_lds_dwordx4 v[250:251], off
	v_lshl_add_u64 v[250:251], v[200:201], 0, s[44:45]
	s_add_i32 m0, s0, 0x2000
	s_nop 0
	global_load_lds_dwordx4 v[250:251], off
	s_mov_b32 m0, s65
	v_lshl_add_u64 v[204:205], v[202:203], 0, s[38:39]
	global_load_lds_dwordx4 v[204:205], off
	v_lshl_add_u64 v[202:203], v[202:203], 0, s[40:41]
	s_mov_b32 m0, s66
	s_nop 0
	global_load_lds_dwordx4 v[202:203], off
	s_waitcnt vmcnt(8)
	s_waitcnt lgkmcnt(0)
	s_barrier
	s_setprio 1
	v_mfma_f32_16x16x32_bf16 v[94:97], v[130:133], v[146:149], v[94:97]
	v_mfma_f32_16x16x32_bf16 v[90:93], v[138:141], v[146:149], v[90:93]
	v_mfma_f32_16x16x32_bf16 v[86:89], v[130:133], v[154:157], v[86:89]
	v_mfma_f32_16x16x32_bf16 v[82:85], v[138:141], v[154:157], v[82:85]
	v_mfma_f32_16x16x32_bf16 v[78:81], v[130:133], v[162:165], v[78:81]
	v_mfma_f32_16x16x32_bf16 v[74:77], v[138:141], v[162:165], v[74:77]
	v_mfma_f32_16x16x32_bf16 v[70:73], v[130:133], v[170:173], v[70:73]
	v_mfma_f32_16x16x32_bf16 v[66:69], v[138:141], v[170:173], v[66:69]
	v_mfma_f32_16x16x32_bf16 v[94:97], v[134:137], v[150:153], v[94:97]
	v_mfma_f32_16x16x32_bf16 v[90:93], v[142:145], v[150:153], v[90:93]
	v_mfma_f32_16x16x32_bf16 v[86:89], v[134:137], v[158:161], v[86:89]
	v_mfma_f32_16x16x32_bf16 v[82:85], v[142:145], v[158:161], v[82:85]
	v_mfma_f32_16x16x32_bf16 v[78:81], v[134:137], v[166:169], v[78:81]
	v_mfma_f32_16x16x32_bf16 v[74:77], v[142:145], v[166:169], v[74:77]
	v_mfma_f32_16x16x32_bf16 v[70:73], v[134:137], v[174:177], v[70:73]
	v_mfma_f32_16x16x32_bf16 v[66:69], v[142:145], v[174:177], v[66:69]
	v_mfma_f32_16x16x32_bf16 v[30:33], v[178:181], v[146:149], v[30:33]
	v_mfma_f32_16x16x32_bf16 v[26:29], v[186:189], v[146:149], v[26:29]
	v_mfma_f32_16x16x32_bf16 v[22:25], v[178:181], v[154:157], v[22:25]
	v_mfma_f32_16x16x32_bf16 v[18:21], v[186:189], v[154:157], v[18:21]
	v_mfma_f32_16x16x32_bf16 v[14:17], v[178:181], v[162:165], v[14:17]
	v_mfma_f32_16x16x32_bf16 v[10:13], v[186:189], v[162:165], v[10:13]
	v_mfma_f32_16x16x32_bf16 v[6:9], v[178:181], v[170:173], v[6:9]
	v_mfma_f32_16x16x32_bf16 v[2:5], v[186:189], v[170:173], v[2:5]
	v_mfma_f32_16x16x32_bf16 v[30:33], v[182:185], v[150:153], v[30:33]
	v_mfma_f32_16x16x32_bf16 v[26:29], v[190:193], v[150:153], v[26:29]
	v_mfma_f32_16x16x32_bf16 v[22:25], v[182:185], v[158:161], v[22:25]
	v_mfma_f32_16x16x32_bf16 v[18:21], v[190:193], v[158:161], v[18:21]
	v_mfma_f32_16x16x32_bf16 v[14:17], v[182:185], v[166:169], v[14:17]
	v_mfma_f32_16x16x32_bf16 v[10:13], v[190:193], v[166:169], v[10:13]
	v_mfma_f32_16x16x32_bf16 v[6:9], v[182:185], v[174:177], v[6:9]
	v_mfma_f32_16x16x32_bf16 v[2:5], v[190:193], v[174:177], v[2:5]
	s_setprio 0
	s_add_i32 s86, s86, 2
	s_add_u32 s62, s62, 0x100
	s_addc_u32 s63, s63, 0
	s_add_u32 s60, s60, 0x100
	s_addc_u32 s61, s61, 0
	s_cmp_gt_u32 s86, 13
	s_barrier
	s_cbranch_scc0 .LBB0_1706
	s_mov_b32 s98, 1
	s_and_b64 vcc, exec, s[46:47]
	s_cbranch_vccz .LBB0_1709
	s_barrier

.LBB0_1785:
	global_load_dword v17, v18, s[12:13] sc1
	s_waitcnt lgkmcnt(0)
	global_load_dword v2, v18, s[14:15] sc1
	global_load_dword v3, v18, s[16:17] sc1
	global_load_dword v4, v18, s[18:19] sc1
	global_load_dword v5, v18, s[20:21] sc1
	global_load_dword v6, v18, s[22:23] sc1
	global_load_dword v7, v18, s[30:31] sc1
	global_load_dword v8, v18, s[34:35] sc1
	global_load_dword v9, v18, s[36:37] sc1
	global_load_dword v10, v18, s[38:39] sc1
	global_load_dword v11, v18, s[40:41] sc1
	global_load_dword v12, v18, s[42:43] sc1
	global_load_dword v13, v18, s[44:45] sc1
	global_load_dword v14, v18, s[46:47] sc1
	global_load_dword v15, v18, s[48:49] sc1
	global_load_dword v16, v18, s[50:51] sc1
	s_mov_b64 s[52:53], -1
	s_mov_b64 s[54:55], -1
	s_waitcnt vmcnt(14)
	v_add_u32_e32 v19, v2, v17
	s_waitcnt vmcnt(13)
	v_add_u32_e32 v19, v19, v3
	s_waitcnt vmcnt(12)
	v_add_u32_e32 v19, v19, v4
	s_waitcnt vmcnt(11)
	v_add_u32_e32 v19, v19, v5
	s_waitcnt vmcnt(10)
	v_add_u32_e32 v19, v19, v6
	s_waitcnt vmcnt(9)
	v_add_u32_e32 v19, v19, v7
	s_waitcnt vmcnt(8)
	v_add_u32_e32 v19, v19, v8
	s_waitcnt vmcnt(7)
	v_add_u32_e32 v19, v19, v9
	s_waitcnt vmcnt(6)
	v_add_u32_e32 v19, v19, v10
	s_waitcnt vmcnt(5)
	v_add_u32_e32 v19, v19, v11
	s_waitcnt vmcnt(4)
	v_add_u32_e32 v19, v19, v12
	s_waitcnt vmcnt(3)
	v_add_u32_e32 v19, v19, v13
	s_waitcnt vmcnt(2)
	v_add_u32_e32 v19, v19, v14
	s_waitcnt vmcnt(1)
	v_add_u32_e32 v19, v19, v15
	s_waitcnt vmcnt(0)
	v_add_u32_e32 v19, v19, v16
	v_cmp_eq_u32_e32 vcc, s0, v19
	s_cbranch_vccnz .LBB0_1784
	s_and_b32 s3, s1, 0xff
	s_cmp_eq_u32 s3, 0
	s_mov_b64 s[56:57], -1
	s_cbranch_scc1 .LBB0_1789
	s_and_b64 vcc, exec, s[56:57]
	s_cbranch_vccz .LBB0_1784

.LBB0_1803:
	s_and_b32 s1, s0, 0xff
	s_mov_b64 s[28:29], -1
	s_cmp_lg_u32 s1, 0
	s_mov_b64 s[34:35], -1
	s_cbranch_scc0 .LBB0_1806
	s_and_b64 vcc, exec, s[34:35]
	s_cbranch_vccz .LBB0_1802

.LBB0_1820:
	s_and_b32 s1, s0, 0xff
	s_cmp_lg_u32 s1, 0
	s_mov_b64 s[28:29], -1
	s_cbranch_scc0 .LBB0_1823
	s_mov_b64 s[30:31], -1
	s_and_b64 vcc, exec, s[28:29]
	s_cbranch_vccz .LBB0_1819

.LBB0_1870:
	global_load_dword v2, v1, s[2:3] sc1
	s_mov_b64 s[4:5], -1
	s_waitcnt vmcnt(0)
	v_cmp_lt_u32_e32 vcc, 3, v2
	s_cbranch_vccnz .LBB0_1869
	global_load_dword v2, v1, s[2:3] sc1
	s_waitcnt vmcnt(0)
	v_cmp_gt_u32_e32 vcc, 4, v2
	s_cbranch_vccz .LBB0_1869
	global_load_dword v2, v1, s[2:3] sc1
	s_waitcnt vmcnt(0)
	v_cmp_gt_u32_e32 vcc, 4, v2
	s_cbranch_vccz .LBB0_1869
	global_load_dword v2, v1, s[2:3] sc1
	s_waitcnt vmcnt(0)
	v_cmp_gt_u32_e32 vcc, 4, v2
	s_cbranch_vccz .LBB0_1869
	global_load_dword v2, v1, s[2:3] sc1
	s_waitcnt vmcnt(0)
	v_cmp_gt_u32_e32 vcc, 4, v2
	s_cbranch_vccz .LBB0_1869
	s_add_i32 s14, s14, -5
	s_cmp_eq_u32 s14, 0
	s_cselect_b64 s[4:5], -1, 0
	s_branch .LBB0_1869
